# k30 + K-loop head reorder in the six GEMM loops: first four LDS fragment reads issued before the pointer/select SALU chain
# speedup vs baseline: 1.0028x; 1.0028x over previous
; #define PG8_STAGE(bufoff, gbase, voff) do { _Pragma("unroll") for (int _i = 0; _i < 2; ++_i) \
;         __builtin_amdgcn_global_load_lds((const unsigned*)((const char*)(gbase) + (voff)[_i]), (PG8_LAS unsigned*)(lds + (bufoff) + ldsw + _i * 8192), 16, 0, 0); } while (0)
; #define PG8_LDA(dst, b, h) do { _Pragma("unroll") for (int m = 0; m < 4; ++m) _Pragma("unroll") for (int k = 0; k < 2; ++k) dst[m][k] = *(const PG8_LAS bf16x8*)(lds + PG8_SA(b, h) + aoff + m * 2048 + k * 1024); } while (0)
; #define PG8_LDB(dst, b, h) do { _Pragma("unroll") for (int n = 0; n < 2; ++n) _Pragma("unroll") for (int k = 0; k < 2; ++k) dst[n][k] = *(const PG8_LAS bf16x8*)(lds + PG8_SB(b, h) + boff + n * 2048 + k * 1024); } while (0)
; #define PG8_MMA(ai, bj, At, Bt) do { __builtin_amdgcn_s_setprio(1); _Pragma("unroll") for (int m = 0; m < 4; ++m) _Pragma("unroll") for (int n = 0; n < 2; ++n) _Pragma("unroll") for (int k = 0; k < 2; ++k) \
;         acc[ai][bj][m][n] = __builtin_amdgcn_mfma_f32_16x16x32_bf16(Bt[n][k], At[m][k], acc[ai][bj][m][n], 0, 0, 0); __builtin_amdgcn_s_setprio(0); } while (0)
; #define PG8_WAIT_V(n) asm volatile("s_waitcnt vmcnt(" #n ")" ::: "memory")
; #define PG8_WAIT_L(n) asm volatile("s_waitcnt lgkmcnt(" #n ")" ::: "memory")
; #define PG8_BAR __builtin_amdgcn_s_barrier()
; #define PG8_SCHED __builtin_amdgcn_sched_barrier(0)
; template <class Epi>
; __device__ __forceinline__ void gemm_phase(PG8_LAS unsigned char* lds, const Gemm g, const StaticOrder& S, const Epi& E, const int wave_s) {
;     ...
;             const bool last = (t == nt - 2);
;             const char* a1 = cA + (size_t)(t + 1) * kstep;
;             const char* a2 = last ? nA : cA + (size_t)(t + 2) * kstep; const char* b2 = last ? nB : cB + (size_t)(t + 2) * kstep;
;             const char* a3 = a2 + kstep; const char* b3 = b2 + kstep;
;             PG8_LDB(B0, 0, 0); PG8_LDB(B1, 0, 1); PG8_SCHED; PG8_LDA(At, 0, 0); PG8_STAGE(PG8_SA(1, 1), a1 + hstepA, voffA);
;             PG8_WAIT_V(8); PG8_WAIT_L(0); PG8_BAR; PG8_MMA(0, 0, At, B0); PG8_MMA(0, 1, At, B1); PG8_BAR; PG8_SCHED;
;             PG8_LDA(At, 0, 1); PG8_STAGE(PG8_SB(0, 0), b2, voffB); PG8_STAGE(PG8_SB(0, 1), b2 + hstepB, voffB); PG8_STAGE(PG8_SA(0, 0), a2, voffA);
;             PG8_WAIT_V(8); PG8_WAIT_L(0); PG8_BAR; PG8_MMA(1, 0, At, B0); PG8_MMA(1, 1, At, B1); PG8_BAR; PG8_SCHED;
.Lg0_prio_done:
.LBB0_131:
	s_add_i32 s61, 0, 0x10000
	v_add_u32_e32 v142, s61, v97
	ds_read_b128 v[130:133], v142
	ds_read_b128 v[134:137], v142 offset:1024
	ds_read_b128 v[138:141], v142 offset:2048
	ds_read_b128 v[142:145], v142 offset:3072
	s_add_i32 s46, s6, 2
	s_add_u32 s47, s44, 0x80
	s_addc_u32 s7, s45, 0
	s_cmp_eq_u32 s40, s6
	s_cselect_b32 s7, s91, s7
	s_cselect_b32 s6, s90, s47
	s_cselect_b32 s73, s93, s13
	s_cselect_b32 s72, s92, s12
	s_add_i32 s47, 0, 0x14000
	v_add_u32_e32 v158, s47, v97
	ds_read_b128 v[146:149], v158
	ds_read_b128 v[150:153], v158 offset:1024
	ds_read_b128 v[154:157], v158 offset:2048
	ds_read_b128 v[158:161], v158 offset:3072
	v_lshl_add_u64 v[194:195], s[44:45], 0, v[224:225]
	s_add_i32 m0, s9, 0xc000
	ds_read_b128 v[162:165], v232
	ds_read_b128 v[166:169], v232 offset:1024
	ds_read_b128 v[170:173], v232 offset:2048
	ds_read_b128 v[174:177], v232 offset:3072
	ds_read_b128 v[178:181], v232 offset:4096
	ds_read_b128 v[182:185], v232 offset:5120
	ds_read_b128 v[186:189], v232 offset:6144
	ds_read_b128 v[190:193], v232 offset:7168
	global_load_lds_dwordx4 v[194:195], off
	v_lshl_add_u64 v[194:195], s[44:45], 0, v[226:227]
	s_add_i32 m0, s9, 0xe000
	s_nop 0
	global_load_lds_dwordx4 v[194:195], off
	s_waitcnt vmcnt(8)
	s_waitcnt lgkmcnt(0)
	s_barrier
	s_waitcnt lgkmcnt(0)
	v_mfma_f32_16x16x32_bf16 v[126:129], v[130:133], v[162:165], v[126:129]
	v_mfma_f32_16x16x32_bf16 v[122:125], v[138:141], v[162:165], v[122:125]
	v_mfma_f32_16x16x32_bf16 v[110:113], v[130:133], v[170:173], v[110:113]
	v_mfma_f32_16x16x32_bf16 v[106:109], v[138:141], v[170:173], v[106:109]
	v_mfma_f32_16x16x32_bf16 v[92:95], v[130:133], v[178:181], v[92:95]
	v_mfma_f32_16x16x32_bf16 v[88:91], v[138:141], v[178:181], v[88:91]
	v_mfma_f32_16x16x32_bf16 v[76:79], v[130:133], v[186:189], v[76:79]
	v_mfma_f32_16x16x32_bf16 v[72:75], v[138:141], v[186:189], v[72:75]
	v_mfma_f32_16x16x32_bf16 v[126:129], v[134:137], v[166:169], v[126:129]
	v_mfma_f32_16x16x32_bf16 v[122:125], v[142:145], v[166:169], v[122:125]
	v_mfma_f32_16x16x32_bf16 v[110:113], v[134:137], v[174:177], v[110:113]
	v_mfma_f32_16x16x32_bf16 v[106:109], v[142:145], v[174:177], v[106:109]
	v_mfma_f32_16x16x32_bf16 v[92:95], v[134:137], v[182:185], v[92:95]
	v_mfma_f32_16x16x32_bf16 v[88:91], v[142:145], v[182:185], v[88:91]
	v_mfma_f32_16x16x32_bf16 v[76:79], v[134:137], v[190:193], v[76:79]
	v_mfma_f32_16x16x32_bf16 v[72:75], v[142:145], v[190:193], v[72:75]
	v_mfma_f32_16x16x32_bf16 v[118:121], v[146:149], v[162:165], v[118:121]
	v_mfma_f32_16x16x32_bf16 v[114:117], v[154:157], v[162:165], v[114:117]
	v_mfma_f32_16x16x32_bf16 v[102:105], v[146:149], v[170:173], v[102:105]
	v_mfma_f32_16x16x32_bf16 v[98:101], v[154:157], v[170:173], v[98:101]
	v_mfma_f32_16x16x32_bf16 v[84:87], v[146:149], v[178:181], v[84:87]
	v_mfma_f32_16x16x32_bf16 v[80:83], v[154:157], v[178:181], v[80:83]
	v_mfma_f32_16x16x32_bf16 v[68:71], v[146:149], v[186:189], v[68:71]
	v_mfma_f32_16x16x32_bf16 v[64:67], v[154:157], v[186:189], v[64:67]
	v_mfma_f32_16x16x32_bf16 v[118:121], v[150:153], v[166:169], v[118:121]
	v_mfma_f32_16x16x32_bf16 v[114:117], v[158:161], v[166:169], v[114:117]
	v_mfma_f32_16x16x32_bf16 v[102:105], v[150:153], v[174:177], v[102:105]
	v_mfma_f32_16x16x32_bf16 v[98:101], v[158:161], v[174:177], v[98:101]
	v_mfma_f32_16x16x32_bf16 v[84:87], v[150:153], v[182:185], v[84:87]
	v_mfma_f32_16x16x32_bf16 v[80:83], v[158:161], v[182:185], v[80:83]
	v_mfma_f32_16x16x32_bf16 v[68:71], v[150:153], v[190:193], v[68:71]
	v_mfma_f32_16x16x32_bf16 v[64:67], v[158:161], v[190:193], v[64:67]
	s_barrier
	s_add_i32 s61, s61, s5
	v_lshl_add_u64 v[194:195], s[72:73], 0, v[210:211]
	s_mov_b32 m0, s61
	ds_read_b128 v[162:165], v232 offset:16384
	ds_read_b128 v[166:169], v232 offset:17408
	ds_read_b128 v[170:173], v232 offset:18432
	ds_read_b128 v[174:177], v232 offset:19456
	ds_read_b128 v[178:181], v232 offset:20480
	ds_read_b128 v[182:185], v232 offset:21504
	ds_read_b128 v[186:189], v232 offset:22528
	ds_read_b128 v[190:193], v232 offset:23552
	global_load_lds_dwordx4 v[194:195], off
	s_add_i32 m0, s61, 0x2000
	v_lshl_add_u64 v[196:197], s[72:73], 0, v[222:223]
	s_add_u32 s72, s72, s50
	s_addc_u32 s73, s73, s51
	s_add_i32 s47, s47, s5
	global_load_lds_dwordx4 v[196:197], off
	v_lshl_add_u64 v[198:199], s[72:73], 0, v[210:211]
	s_mov_b32 m0, s47
	v_lshl_add_u64 v[200:201], s[72:73], 0, v[222:223]
	global_load_lds_dwordx4 v[198:199], off
	s_add_i32 m0, s47, 0x2000
	v_lshl_add_u64 v[202:203], s[6:7], 0, v[218:219]
	global_load_lds_dwordx4 v[200:201], off
	s_mov_b32 m0, s9
	v_lshl_add_u64 v[204:205], s[6:7], 0, v[220:221]
	global_load_lds_dwordx4 v[202:203], off
	s_mov_b32 m0, s10
	s_nop 0
	global_load_lds_dwordx4 v[204:205], off
	s_waitcnt vmcnt(8)
	s_waitcnt lgkmcnt(0)
	s_barrier
; #define PG8_STAGE(bufoff, gbase, voff) do { _Pragma("unroll") for (int _i = 0; _i < 2; ++_i) \
;         __builtin_amdgcn_global_load_lds((const unsigned*)((const char*)(gbase) + (voff)[_i]), (PG8_LAS unsigned*)(lds + (bufoff) + ldsw + _i * 8192), 16, 0, 0); } while (0)
; #define PG8_LDA(dst, b, h) do { _Pragma("unroll") for (int m = 0; m < 4; ++m) _Pragma("unroll") for (int k = 0; k < 2; ++k) dst[m][k] = *(const PG8_LAS bf16x8*)(lds + PG8_SA(b, h) + aoff + m * 2048 + k * 1024); } while (0)
; #define PG8_LDB(dst, b, h) do { _Pragma("unroll") for (int n = 0; n < 2; ++n) _Pragma("unroll") for (int k = 0; k < 2; ++k) dst[n][k] = *(const PG8_LAS bf16x8*)(lds + PG8_SB(b, h) + boff + n * 2048 + k * 1024); } while (0)
; #define PG8_MMA(ai, bj, At, Bt) do { __builtin_amdgcn_s_setprio(1); _Pragma("unroll") for (int m = 0; m < 4; ++m) _Pragma("unroll") for (int n = 0; n < 2; ++n) _Pragma("unroll") for (int k = 0; k < 2; ++k) \
;         acc[ai][bj][m][n] = __builtin_amdgcn_mfma_f32_16x16x32_bf16(Bt[n][k], At[m][k], acc[ai][bj][m][n], 0, 0, 0); __builtin_amdgcn_s_setprio(0); } while (0)
; #define PG8_WAIT_V(n) asm volatile("s_waitcnt vmcnt(" #n ")" ::: "memory")
; #define PG8_WAIT_L(n) asm volatile("s_waitcnt lgkmcnt(" #n ")" ::: "memory")
; #define PG8_BAR __builtin_amdgcn_s_barrier()
; #define PG8_SCHED __builtin_amdgcn_sched_barrier(0)
; template <class Epi>
; __device__ __forceinline__ void gemm_phase(PG8_LAS unsigned char* lds, const Gemm g, const StaticOrder& S, const Epi& E, const int wave_s) {
;     ...
;             PG8_WAIT_V(8); PG8_WAIT_L(0); PG8_BAR; PG8_MMA(1, 0, At, B0); PG8_MMA(1, 1, At, B1); PG8_BAR; PG8_SCHED;
;             PG8_LDB(B0, 1, 0); PG8_LDB(B1, 1, 1); PG8_SCHED; PG8_LDA(At, 1, 0); PG8_STAGE(PG8_SA(0, 1), a2 + hstepA, voffA);
;             PG8_WAIT_V(8); PG8_WAIT_L(0); PG8_BAR; PG8_MMA(0, 0, At, B0); PG8_MMA(0, 1, At, B1); PG8_BAR; PG8_SCHED;
	s_waitcnt lgkmcnt(0)
	v_mfma_f32_16x16x32_bf16 v[60:63], v[130:133], v[162:165], v[60:63]
	v_mfma_f32_16x16x32_bf16 v[56:59], v[138:141], v[162:165], v[56:59]
	v_mfma_f32_16x16x32_bf16 v[44:47], v[130:133], v[170:173], v[44:47]
	v_mfma_f32_16x16x32_bf16 v[40:43], v[138:141], v[170:173], v[40:43]
	v_mfma_f32_16x16x32_bf16 v[28:31], v[130:133], v[178:181], v[28:31]
	v_mfma_f32_16x16x32_bf16 v[24:27], v[138:141], v[178:181], v[24:27]
	v_mfma_f32_16x16x32_bf16 v[12:15], v[130:133], v[186:189], v[12:15]
	v_mfma_f32_16x16x32_bf16 v[8:11], v[138:141], v[186:189], v[8:11]
	v_mfma_f32_16x16x32_bf16 v[60:63], v[134:137], v[166:169], v[60:63]
	v_mfma_f32_16x16x32_bf16 v[56:59], v[142:145], v[166:169], v[56:59]
	v_mfma_f32_16x16x32_bf16 v[44:47], v[134:137], v[174:177], v[44:47]
	v_mfma_f32_16x16x32_bf16 v[40:43], v[142:145], v[174:177], v[40:43]
	v_mfma_f32_16x16x32_bf16 v[28:31], v[134:137], v[182:185], v[28:31]
	v_mfma_f32_16x16x32_bf16 v[24:27], v[142:145], v[182:185], v[24:27]
	v_mfma_f32_16x16x32_bf16 v[12:15], v[134:137], v[190:193], v[12:15]
	v_mfma_f32_16x16x32_bf16 v[8:11], v[142:145], v[190:193], v[8:11]
	v_mfma_f32_16x16x32_bf16 v[52:55], v[146:149], v[162:165], v[52:55]
	v_mfma_f32_16x16x32_bf16 v[48:51], v[154:157], v[162:165], v[48:51]
	v_mfma_f32_16x16x32_bf16 v[36:39], v[146:149], v[170:173], v[36:39]
	v_mfma_f32_16x16x32_bf16 v[32:35], v[154:157], v[170:173], v[32:35]
	v_mfma_f32_16x16x32_bf16 v[20:23], v[146:149], v[178:181], v[20:23]
	v_mfma_f32_16x16x32_bf16 v[16:19], v[154:157], v[178:181], v[16:19]
	v_mfma_f32_16x16x32_bf16 v[4:7], v[146:149], v[186:189], v[4:7]
	v_mfma_f32_16x16x32_bf16 v[0:3], v[154:157], v[186:189], v[0:3]
	v_mfma_f32_16x16x32_bf16 v[52:55], v[150:153], v[166:169], v[52:55]
	v_mfma_f32_16x16x32_bf16 v[48:51], v[158:161], v[166:169], v[48:51]
	v_mfma_f32_16x16x32_bf16 v[36:39], v[150:153], v[174:177], v[36:39]
	v_mfma_f32_16x16x32_bf16 v[32:35], v[158:161], v[174:177], v[32:35]
	v_mfma_f32_16x16x32_bf16 v[20:23], v[150:153], v[182:185], v[20:23]
	v_mfma_f32_16x16x32_bf16 v[16:19], v[158:161], v[182:185], v[16:19]
	v_mfma_f32_16x16x32_bf16 v[4:7], v[150:153], v[190:193], v[4:7]
	v_mfma_f32_16x16x32_bf16 v[0:3], v[158:161], v[190:193], v[0:3]
	s_barrier
	s_add_i32 s47, 0, 0x18000
	s_add_i32 s61, 0, 0x1c000
	v_add_u32_e32 v142, s47, v97
	v_add_u32_e32 v158, s61, v97
	ds_read_b128 v[130:133], v142
	ds_read_b128 v[134:137], v142 offset:1024
	ds_read_b128 v[138:141], v142 offset:2048
	ds_read_b128 v[142:145], v142 offset:3072
	ds_read_b128 v[146:149], v158
	ds_read_b128 v[150:153], v158 offset:1024
	ds_read_b128 v[154:157], v158 offset:2048
	ds_read_b128 v[158:161], v158 offset:3072
	s_add_u32 s6, s6, s48
	s_addc_u32 s7, s7, s49
	s_mov_b32 m0, s11
	v_lshl_add_u64 v[206:207], s[6:7], 0, v[218:219]
	ds_read_b128 v[162:165], v232 offset:32768
	ds_read_b128 v[166:169], v232 offset:33792
	ds_read_b128 v[170:173], v232 offset:34816
	ds_read_b128 v[174:177], v232 offset:35840
	ds_read_b128 v[178:181], v232 offset:36864
	ds_read_b128 v[182:185], v232 offset:37888
	ds_read_b128 v[186:189], v232 offset:38912
	ds_read_b128 v[190:193], v232 offset:39936
	global_load_lds_dwordx4 v[206:207], off
	v_lshl_add_u64 v[206:207], s[6:7], 0, v[220:221]
	s_mov_b32 m0, s16
	s_nop 0
	global_load_lds_dwordx4 v[206:207], off
	s_waitcnt vmcnt(8)
	s_waitcnt lgkmcnt(0)
	s_barrier
	s_waitcnt lgkmcnt(0)
	v_mfma_f32_16x16x32_bf16 v[126:129], v[130:133], v[162:165], v[126:129]
	v_mfma_f32_16x16x32_bf16 v[122:125], v[138:141], v[162:165], v[122:125]
	v_mfma_f32_16x16x32_bf16 v[110:113], v[130:133], v[170:173], v[110:113]
	v_mfma_f32_16x16x32_bf16 v[106:109], v[138:141], v[170:173], v[106:109]
	v_mfma_f32_16x16x32_bf16 v[92:95], v[130:133], v[178:181], v[92:95]
	v_mfma_f32_16x16x32_bf16 v[88:91], v[138:141], v[178:181], v[88:91]
	v_mfma_f32_16x16x32_bf16 v[76:79], v[130:133], v[186:189], v[76:79]
	v_mfma_f32_16x16x32_bf16 v[72:75], v[138:141], v[186:189], v[72:75]
	v_mfma_f32_16x16x32_bf16 v[126:129], v[134:137], v[166:169], v[126:129]
	v_mfma_f32_16x16x32_bf16 v[122:125], v[142:145], v[166:169], v[122:125]
	v_mfma_f32_16x16x32_bf16 v[110:113], v[134:137], v[174:177], v[110:113]
	v_mfma_f32_16x16x32_bf16 v[106:109], v[142:145], v[174:177], v[106:109]
	v_mfma_f32_16x16x32_bf16 v[92:95], v[134:137], v[182:185], v[92:95]
	v_mfma_f32_16x16x32_bf16 v[88:91], v[142:145], v[182:185], v[88:91]
	v_mfma_f32_16x16x32_bf16 v[76:79], v[134:137], v[190:193], v[76:79]
	v_mfma_f32_16x16x32_bf16 v[72:75], v[142:145], v[190:193], v[72:75]
	v_mfma_f32_16x16x32_bf16 v[118:121], v[146:149], v[162:165], v[118:121]
	v_mfma_f32_16x16x32_bf16 v[114:117], v[154:157], v[162:165], v[114:117]
	v_mfma_f32_16x16x32_bf16 v[102:105], v[146:149], v[170:173], v[102:105]
	v_mfma_f32_16x16x32_bf16 v[98:101], v[154:157], v[170:173], v[98:101]
	v_mfma_f32_16x16x32_bf16 v[84:87], v[146:149], v[178:181], v[84:87]
	v_mfma_f32_16x16x32_bf16 v[80:83], v[154:157], v[178:181], v[80:83]
	v_mfma_f32_16x16x32_bf16 v[68:71], v[146:149], v[186:189], v[68:71]
	v_mfma_f32_16x16x32_bf16 v[64:67], v[154:157], v[186:189], v[64:67]
	v_mfma_f32_16x16x32_bf16 v[118:121], v[150:153], v[166:169], v[118:121]
	v_mfma_f32_16x16x32_bf16 v[114:117], v[158:161], v[166:169], v[114:117]
	v_mfma_f32_16x16x32_bf16 v[102:105], v[150:153], v[174:177], v[102:105]
	v_mfma_f32_16x16x32_bf16 v[98:101], v[158:161], v[174:177], v[98:101]
	v_mfma_f32_16x16x32_bf16 v[84:87], v[150:153], v[182:185], v[84:87]
	v_mfma_f32_16x16x32_bf16 v[80:83], v[158:161], v[182:185], v[80:83]
	v_mfma_f32_16x16x32_bf16 v[68:71], v[150:153], v[190:193], v[68:71]
	v_mfma_f32_16x16x32_bf16 v[64:67], v[158:161], v[190:193], v[64:67]
	s_barrier
; #define PG8_STAGE(bufoff, gbase, voff) do { _Pragma("unroll") for (int _i = 0; _i < 2; ++_i) \
;         __builtin_amdgcn_global_load_lds((const unsigned*)((const char*)(gbase) + (voff)[_i]), (PG8_LAS unsigned*)(lds + (bufoff) + ldsw + _i * 8192), 16, 0, 0); } while (0)
; #define PG8_LDA(dst, b, h) do { _Pragma("unroll") for (int m = 0; m < 4; ++m) _Pragma("unroll") for (int k = 0; k < 2; ++k) dst[m][k] = *(const PG8_LAS bf16x8*)(lds + PG8_SA(b, h) + aoff + m * 2048 + k * 1024); } while (0)
; #define PG8_MMA(ai, bj, At, Bt) do { __builtin_amdgcn_s_setprio(1); _Pragma("unroll") for (int m = 0; m < 4; ++m) _Pragma("unroll") for (int n = 0; n < 2; ++n) _Pragma("unroll") for (int k = 0; k < 2; ++k) \
;         acc[ai][bj][m][n] = __builtin_amdgcn_mfma_f32_16x16x32_bf16(Bt[n][k], At[m][k], acc[ai][bj][m][n], 0, 0, 0); __builtin_amdgcn_s_setprio(0); } while (0)
; #define PG8_WAIT_V(n) asm volatile("s_waitcnt vmcnt(" #n ")" ::: "memory")
; #define PG8_WAIT_L(n) asm volatile("s_waitcnt lgkmcnt(" #n ")" ::: "memory")
; #define PG8_BAR __builtin_amdgcn_s_barrier()
; #define PG8_SCHED __builtin_amdgcn_sched_barrier(0)
; template <class Epi>
; __device__ __forceinline__ void gemm_phase(PG8_LAS unsigned char* lds, const Gemm g, const StaticOrder& S, const Epi& E, const int wave_s) {
;     ...
;             PG8_LDA(At, 1, 1); PG8_STAGE(PG8_SB(1, 0), b3, voffB); PG8_STAGE(PG8_SB(1, 1), b3 + hstepB, voffB); PG8_STAGE(PG8_SA(1, 0), a3, voffA);
;             PG8_WAIT_V(8); PG8_WAIT_L(0); PG8_BAR; PG8_MMA(1, 0, At, B0); PG8_MMA(1, 1, At, B1); PG8_BAR; PG8_SCHED;
;         }
	s_add_i32 s6, s47, s5
	v_lshl_add_u64 v[194:195], v[194:195], 0, s[52:53]
	s_mov_b32 m0, s6
	ds_read_b128 v[162:165], v232 offset:49152
	ds_read_b128 v[166:169], v232 offset:50176
	ds_read_b128 v[170:173], v232 offset:51200
	ds_read_b128 v[174:177], v232 offset:52224
	ds_read_b128 v[178:181], v232 offset:53248
	ds_read_b128 v[182:185], v232 offset:54272
	ds_read_b128 v[186:189], v232 offset:55296
	ds_read_b128 v[190:193], v232 offset:56320
	global_load_lds_dwordx4 v[194:195], off
	v_lshl_add_u64 v[194:195], v[196:197], 0, s[52:53]
	s_add_i32 m0, s6, 0x2000
	s_add_i32 s6, s61, s5
	global_load_lds_dwordx4 v[194:195], off
	v_lshl_add_u64 v[194:195], v[198:199], 0, s[52:53]
	s_mov_b32 m0, s6
	s_nop 0
	global_load_lds_dwordx4 v[194:195], off
	v_lshl_add_u64 v[194:195], v[200:201], 0, s[52:53]
	s_add_i32 m0, s6, 0x2000
	s_nop 0
	global_load_lds_dwordx4 v[194:195], off
	v_lshl_add_u64 v[194:195], v[202:203], 0, s[52:53]
	s_mov_b32 m0, s38
	s_nop 0
	global_load_lds_dwordx4 v[194:195], off
	v_lshl_add_u64 v[194:195], v[204:205], 0, s[52:53]
	s_mov_b32 m0, s39
	s_nop 0
	global_load_lds_dwordx4 v[194:195], off
	s_waitcnt vmcnt(8)
	s_waitcnt lgkmcnt(0)
	s_barrier
	s_waitcnt lgkmcnt(0)
	v_mfma_f32_16x16x32_bf16 v[60:63], v[130:133], v[162:165], v[60:63]
	v_mfma_f32_16x16x32_bf16 v[56:59], v[138:141], v[162:165], v[56:59]
	s_add_u32 s44, s44, 0x100
	s_addc_u32 s45, s45, 0
	s_add_u32 s12, s12, 0x100
	s_addc_u32 s13, s13, 0
	s_mov_b32 s6, s46
	s_cmp_ge_i32 s46, s37
	v_mfma_f32_16x16x32_bf16 v[44:47], v[130:133], v[170:173], v[44:47]
	v_mfma_f32_16x16x32_bf16 v[40:43], v[138:141], v[170:173], v[40:43]
	v_mfma_f32_16x16x32_bf16 v[28:31], v[130:133], v[178:181], v[28:31]
	v_mfma_f32_16x16x32_bf16 v[24:27], v[138:141], v[178:181], v[24:27]
	v_mfma_f32_16x16x32_bf16 v[12:15], v[130:133], v[186:189], v[12:15]
	v_mfma_f32_16x16x32_bf16 v[8:11], v[138:141], v[186:189], v[8:11]
	v_mfma_f32_16x16x32_bf16 v[60:63], v[134:137], v[166:169], v[60:63]
	v_mfma_f32_16x16x32_bf16 v[56:59], v[142:145], v[166:169], v[56:59]
	v_mfma_f32_16x16x32_bf16 v[44:47], v[134:137], v[174:177], v[44:47]
	v_mfma_f32_16x16x32_bf16 v[40:43], v[142:145], v[174:177], v[40:43]
	v_mfma_f32_16x16x32_bf16 v[28:31], v[134:137], v[182:185], v[28:31]
	v_mfma_f32_16x16x32_bf16 v[24:27], v[142:145], v[182:185], v[24:27]
	v_mfma_f32_16x16x32_bf16 v[12:15], v[134:137], v[190:193], v[12:15]
	v_mfma_f32_16x16x32_bf16 v[8:11], v[142:145], v[190:193], v[8:11]
	v_mfma_f32_16x16x32_bf16 v[52:55], v[146:149], v[162:165], v[52:55]
	v_mfma_f32_16x16x32_bf16 v[48:51], v[154:157], v[162:165], v[48:51]
	v_mfma_f32_16x16x32_bf16 v[36:39], v[146:149], v[170:173], v[36:39]
	v_mfma_f32_16x16x32_bf16 v[32:35], v[154:157], v[170:173], v[32:35]
	v_mfma_f32_16x16x32_bf16 v[20:23], v[146:149], v[178:181], v[20:23]
	v_mfma_f32_16x16x32_bf16 v[16:19], v[154:157], v[178:181], v[16:19]
	v_mfma_f32_16x16x32_bf16 v[4:7], v[146:149], v[186:189], v[4:7]
	v_mfma_f32_16x16x32_bf16 v[0:3], v[154:157], v[186:189], v[0:3]
	v_mfma_f32_16x16x32_bf16 v[52:55], v[150:153], v[166:169], v[52:55]
	v_mfma_f32_16x16x32_bf16 v[48:51], v[158:161], v[166:169], v[48:51]
	v_mfma_f32_16x16x32_bf16 v[36:39], v[150:153], v[174:177], v[36:39]
	v_mfma_f32_16x16x32_bf16 v[32:35], v[158:161], v[174:177], v[32:35]
	v_mfma_f32_16x16x32_bf16 v[20:23], v[150:153], v[182:185], v[20:23]
	v_mfma_f32_16x16x32_bf16 v[16:19], v[158:161], v[182:185], v[16:19]
	v_mfma_f32_16x16x32_bf16 v[4:7], v[150:153], v[190:193], v[4:7]
	v_mfma_f32_16x16x32_bf16 v[0:3], v[158:161], v[190:193], v[0:3]
	s_barrier
	s_cbranch_scc0 .LBB0_131
	s_setprio 0

; #define PG8_STAGE(bufoff, gbase, voff) do { _Pragma("unroll") for (int _i = 0; _i < 2; ++_i) \
;         __builtin_amdgcn_global_load_lds((const unsigned*)((const char*)(gbase) + (voff)[_i]), (PG8_LAS unsigned*)(lds + (bufoff) + ldsw + _i * 8192), 16, 0, 0); } while (0)
; #define PG8_LDA(dst, b, h) do { _Pragma("unroll") for (int m = 0; m < 4; ++m) _Pragma("unroll") for (int k = 0; k < 2; ++k) dst[m][k] = *(const PG8_LAS bf16x8*)(lds + PG8_SA(b, h) + aoff + m * 2048 + k * 1024); } while (0)
; #define PG8_LDB(dst, b, h) do { _Pragma("unroll") for (int n = 0; n < 2; ++n) _Pragma("unroll") for (int k = 0; k < 2; ++k) dst[n][k] = *(const PG8_LAS bf16x8*)(lds + PG8_SB(b, h) + boff + n * 2048 + k * 1024); } while (0)
; #define PG8_MMA(ai, bj, At, Bt) do { __builtin_amdgcn_s_setprio(1); _Pragma("unroll") for (int m = 0; m < 4; ++m) _Pragma("unroll") for (int n = 0; n < 2; ++n) _Pragma("unroll") for (int k = 0; k < 2; ++k) \
;         acc[ai][bj][m][n] = __builtin_amdgcn_mfma_f32_16x16x32_bf16(Bt[n][k], At[m][k], acc[ai][bj][m][n], 0, 0, 0); __builtin_amdgcn_s_setprio(0); } while (0)
; #define PG8_WAIT_V(n) asm volatile("s_waitcnt vmcnt(" #n ")" ::: "memory")
; #define PG8_WAIT_L(n) asm volatile("s_waitcnt lgkmcnt(" #n ")" ::: "memory")
; #define PG8_BAR __builtin_amdgcn_s_barrier()
; #define PG8_SCHED __builtin_amdgcn_sched_barrier(0)
; template <class Epi>
; __device__ __forceinline__ void gemm_phase(PG8_LAS unsigned char* lds, const Gemm g, const StaticOrder& S, const Epi& E, const int wave_s) {
;     ...
;             const bool last = (t == nt - 2);
;             const char* a1 = cA + (size_t)(t + 1) * kstep;
;             const char* a2 = last ? nA : cA + (size_t)(t + 2) * kstep; const char* b2 = last ? nB : cB + (size_t)(t + 2) * kstep;
;             const char* a3 = a2 + kstep; const char* b3 = b2 + kstep;
;             PG8_LDB(B0, 0, 0); PG8_LDB(B1, 0, 1); PG8_SCHED; PG8_LDA(At, 0, 0); PG8_STAGE(PG8_SA(1, 1), a1 + hstepA, voffA);
;             PG8_WAIT_V(8); PG8_WAIT_L(0); PG8_BAR; PG8_MMA(0, 0, At, B0); PG8_MMA(0, 1, At, B1); PG8_BAR; PG8_SCHED;
;             PG8_LDA(At, 0, 1); PG8_STAGE(PG8_SB(0, 0), b2, voffB); PG8_STAGE(PG8_SB(0, 1), b2 + hstepB, voffB); PG8_STAGE(PG8_SA(0, 0), a2, voffA);
;             PG8_WAIT_V(8); PG8_WAIT_L(0); PG8_BAR; PG8_MMA(1, 0, At, B0); PG8_MMA(1, 1, At, B1); PG8_BAR; PG8_SCHED;
.Lg1_prio_done:
.LBB0_336:
	s_add_i32 s46, 0, 0x10000
	v_add_u32_e32 v154, s46, v97
	ds_read_b128 v[130:133], v154
	ds_read_b128 v[134:137], v154 offset:1024
	ds_read_b128 v[150:153], v154 offset:2048
	ds_read_b128 v[154:157], v154 offset:3072
	s_add_i32 s36, s6, 2
	s_add_u32 s38, s44, 0x80
	s_addc_u32 s7, s45, 0
	s_cmp_eq_u32 s5, s6
	s_cselect_b32 s7, s91, s7
	s_cselect_b32 s6, s90, s38
	s_cselect_b32 s39, s93, s25
	s_cselect_b32 s38, s92, s9
	s_add_i32 s47, 0, 0x14000
	v_add_u32_e32 v171, s47, v97
	ds_read_b128 v[158:161], v171
	ds_read_b128 v[162:165], v171 offset:1024
	ds_read_b128 v[166:169], v171 offset:2048
	ds_read_b128 v[172:175], v171 offset:3072
	v_lshl_add_u64 v[208:209], s[44:45], 0, v[146:147]
	s_add_i32 m0, s13, 0xc000
	ds_read_b128 v[176:179], v170
	ds_read_b128 v[180:183], v170 offset:1024
	ds_read_b128 v[184:187], v170 offset:2048
	ds_read_b128 v[188:191], v170 offset:3072
	ds_read_b128 v[192:195], v170 offset:4096
	ds_read_b128 v[196:199], v170 offset:5120
	ds_read_b128 v[200:203], v170 offset:6144
	ds_read_b128 v[204:207], v170 offset:7168
	global_load_lds_dwordx4 v[208:209], off
	v_lshl_add_u64 v[208:209], s[44:45], 0, v[148:149]
	s_add_i32 m0, s13, 0xe000
	s_nop 0
	global_load_lds_dwordx4 v[208:209], off
	s_waitcnt vmcnt(8)
	s_waitcnt lgkmcnt(0)
	s_barrier
	s_waitcnt lgkmcnt(0)
	v_mfma_f32_16x16x32_bf16 v[122:125], v[130:133], v[176:179], v[122:125]
	v_mfma_f32_16x16x32_bf16 v[126:129], v[150:153], v[176:179], v[126:129]
	v_mfma_f32_16x16x32_bf16 v[110:113], v[130:133], v[184:187], v[110:113]
	v_mfma_f32_16x16x32_bf16 v[106:109], v[150:153], v[184:187], v[106:109]
	v_mfma_f32_16x16x32_bf16 v[92:95], v[130:133], v[192:195], v[92:95]
	v_mfma_f32_16x16x32_bf16 v[88:91], v[150:153], v[192:195], v[88:91]
	v_mfma_f32_16x16x32_bf16 v[76:79], v[130:133], v[200:203], v[76:79]
	v_mfma_f32_16x16x32_bf16 v[72:75], v[150:153], v[200:203], v[72:75]
	v_mfma_f32_16x16x32_bf16 v[122:125], v[134:137], v[180:183], v[122:125]
	v_mfma_f32_16x16x32_bf16 v[126:129], v[154:157], v[180:183], v[126:129]
	v_mfma_f32_16x16x32_bf16 v[110:113], v[134:137], v[188:191], v[110:113]
	v_mfma_f32_16x16x32_bf16 v[106:109], v[154:157], v[188:191], v[106:109]
	v_mfma_f32_16x16x32_bf16 v[92:95], v[134:137], v[196:199], v[92:95]
	v_mfma_f32_16x16x32_bf16 v[88:91], v[154:157], v[196:199], v[88:91]
	v_mfma_f32_16x16x32_bf16 v[76:79], v[134:137], v[204:207], v[76:79]
	v_mfma_f32_16x16x32_bf16 v[72:75], v[154:157], v[204:207], v[72:75]
	v_mfma_f32_16x16x32_bf16 v[118:121], v[158:161], v[176:179], v[118:121]
	v_mfma_f32_16x16x32_bf16 v[114:117], v[166:169], v[176:179], v[114:117]
	v_mfma_f32_16x16x32_bf16 v[102:105], v[158:161], v[184:187], v[102:105]
	v_mfma_f32_16x16x32_bf16 v[98:101], v[166:169], v[184:187], v[98:101]
	v_mfma_f32_16x16x32_bf16 v[84:87], v[158:161], v[192:195], v[84:87]
	v_mfma_f32_16x16x32_bf16 v[80:83], v[166:169], v[192:195], v[80:83]
	v_mfma_f32_16x16x32_bf16 v[68:71], v[158:161], v[200:203], v[68:71]
	v_mfma_f32_16x16x32_bf16 v[64:67], v[166:169], v[200:203], v[64:67]
	v_mfma_f32_16x16x32_bf16 v[118:121], v[162:165], v[180:183], v[118:121]
	v_mfma_f32_16x16x32_bf16 v[114:117], v[172:175], v[180:183], v[114:117]
	v_mfma_f32_16x16x32_bf16 v[102:105], v[162:165], v[188:191], v[102:105]
	v_mfma_f32_16x16x32_bf16 v[98:101], v[172:175], v[188:191], v[98:101]
	v_mfma_f32_16x16x32_bf16 v[84:87], v[162:165], v[196:199], v[84:87]
	v_mfma_f32_16x16x32_bf16 v[80:83], v[172:175], v[196:199], v[80:83]
	v_mfma_f32_16x16x32_bf16 v[68:71], v[162:165], v[204:207], v[68:71]
	v_mfma_f32_16x16x32_bf16 v[64:67], v[172:175], v[204:207], v[64:67]
	s_barrier
	s_add_i32 s46, s46, s12
	v_lshl_add_u64 v[208:209], s[38:39], 0, v[140:141]
	s_mov_b32 m0, s46
	ds_read_b128 v[176:179], v170 offset:16384
	ds_read_b128 v[180:183], v170 offset:17408
	ds_read_b128 v[184:187], v170 offset:18432
	ds_read_b128 v[188:191], v170 offset:19456
	ds_read_b128 v[192:195], v170 offset:20480
	ds_read_b128 v[196:199], v170 offset:21504
	ds_read_b128 v[200:203], v170 offset:22528
	ds_read_b128 v[204:207], v170 offset:23552
	global_load_lds_dwordx4 v[208:209], off
	s_add_i32 m0, s46, 0x2000
	v_lshl_add_u64 v[218:219], s[38:39], 0, v[144:145]
	s_add_u32 s38, s38, s62
	s_addc_u32 s39, s39, s63
	s_add_i32 s46, s47, s12
	global_load_lds_dwordx4 v[218:219], off
	v_lshl_add_u64 v[220:221], s[38:39], 0, v[140:141]
	s_mov_b32 m0, s46
	v_lshl_add_u64 v[222:223], s[38:39], 0, v[144:145]
	global_load_lds_dwordx4 v[220:221], off
	s_add_i32 m0, s46, 0x2000
	v_lshl_add_u64 v[224:225], s[6:7], 0, v[138:139]
	global_load_lds_dwordx4 v[222:223], off
	s_mov_b32 m0, s13
	v_lshl_add_u64 v[226:227], s[6:7], 0, v[142:143]
	global_load_lds_dwordx4 v[224:225], off
	s_mov_b32 m0, s40
	s_nop 0
	global_load_lds_dwordx4 v[226:227], off
	s_waitcnt vmcnt(8)
	s_waitcnt lgkmcnt(0)
	s_barrier
; #define PG8_STAGE(bufoff, gbase, voff) do { _Pragma("unroll") for (int _i = 0; _i < 2; ++_i) \
;         __builtin_amdgcn_global_load_lds((const unsigned*)((const char*)(gbase) + (voff)[_i]), (PG8_LAS unsigned*)(lds + (bufoff) + ldsw + _i * 8192), 16, 0, 0); } while (0)
; #define PG8_LDA(dst, b, h) do { _Pragma("unroll") for (int m = 0; m < 4; ++m) _Pragma("unroll") for (int k = 0; k < 2; ++k) dst[m][k] = *(const PG8_LAS bf16x8*)(lds + PG8_SA(b, h) + aoff + m * 2048 + k * 1024); } while (0)
; #define PG8_LDB(dst, b, h) do { _Pragma("unroll") for (int n = 0; n < 2; ++n) _Pragma("unroll") for (int k = 0; k < 2; ++k) dst[n][k] = *(const PG8_LAS bf16x8*)(lds + PG8_SB(b, h) + boff + n * 2048 + k * 1024); } while (0)
; #define PG8_MMA(ai, bj, At, Bt) do { __builtin_amdgcn_s_setprio(1); _Pragma("unroll") for (int m = 0; m < 4; ++m) _Pragma("unroll") for (int n = 0; n < 2; ++n) _Pragma("unroll") for (int k = 0; k < 2; ++k) \
;         acc[ai][bj][m][n] = __builtin_amdgcn_mfma_f32_16x16x32_bf16(Bt[n][k], At[m][k], acc[ai][bj][m][n], 0, 0, 0); __builtin_amdgcn_s_setprio(0); } while (0)
; #define PG8_WAIT_V(n) asm volatile("s_waitcnt vmcnt(" #n ")" ::: "memory")
; #define PG8_WAIT_L(n) asm volatile("s_waitcnt lgkmcnt(" #n ")" ::: "memory")
; #define PG8_BAR __builtin_amdgcn_s_barrier()
; #define PG8_SCHED __builtin_amdgcn_sched_barrier(0)
; template <class Epi>
; __device__ __forceinline__ void gemm_phase(PG8_LAS unsigned char* lds, const Gemm g, const StaticOrder& S, const Epi& E, const int wave_s) {
;     ...
;             PG8_WAIT_V(8); PG8_WAIT_L(0); PG8_BAR; PG8_MMA(1, 0, At, B0); PG8_MMA(1, 1, At, B1); PG8_BAR; PG8_SCHED;
;             PG8_LDB(B0, 1, 0); PG8_LDB(B1, 1, 1); PG8_SCHED; PG8_LDA(At, 1, 0); PG8_STAGE(PG8_SA(0, 1), a2 + hstepA, voffA);
;             PG8_WAIT_V(8); PG8_WAIT_L(0); PG8_BAR; PG8_MMA(0, 0, At, B0); PG8_MMA(0, 1, At, B1); PG8_BAR; PG8_SCHED;
	s_waitcnt lgkmcnt(0)
	v_mfma_f32_16x16x32_bf16 v[60:63], v[130:133], v[176:179], v[60:63]
	v_mfma_f32_16x16x32_bf16 v[56:59], v[150:153], v[176:179], v[56:59]
	v_mfma_f32_16x16x32_bf16 v[44:47], v[130:133], v[184:187], v[44:47]
	v_mfma_f32_16x16x32_bf16 v[40:43], v[150:153], v[184:187], v[40:43]
	v_mfma_f32_16x16x32_bf16 v[28:31], v[130:133], v[192:195], v[28:31]
	v_mfma_f32_16x16x32_bf16 v[24:27], v[150:153], v[192:195], v[24:27]
	v_mfma_f32_16x16x32_bf16 v[12:15], v[130:133], v[200:203], v[12:15]
	v_mfma_f32_16x16x32_bf16 v[8:11], v[150:153], v[200:203], v[8:11]
	v_mfma_f32_16x16x32_bf16 v[60:63], v[134:137], v[180:183], v[60:63]
	v_mfma_f32_16x16x32_bf16 v[56:59], v[154:157], v[180:183], v[56:59]
	v_mfma_f32_16x16x32_bf16 v[44:47], v[134:137], v[188:191], v[44:47]
	v_mfma_f32_16x16x32_bf16 v[40:43], v[154:157], v[188:191], v[40:43]
	v_mfma_f32_16x16x32_bf16 v[28:31], v[134:137], v[196:199], v[28:31]
	v_mfma_f32_16x16x32_bf16 v[24:27], v[154:157], v[196:199], v[24:27]
	v_mfma_f32_16x16x32_bf16 v[12:15], v[134:137], v[204:207], v[12:15]
	v_mfma_f32_16x16x32_bf16 v[8:11], v[154:157], v[204:207], v[8:11]
	v_mfma_f32_16x16x32_bf16 v[52:55], v[158:161], v[176:179], v[52:55]
	v_mfma_f32_16x16x32_bf16 v[48:51], v[166:169], v[176:179], v[48:51]
	v_mfma_f32_16x16x32_bf16 v[36:39], v[158:161], v[184:187], v[36:39]
	v_mfma_f32_16x16x32_bf16 v[32:35], v[166:169], v[184:187], v[32:35]
	v_mfma_f32_16x16x32_bf16 v[20:23], v[158:161], v[192:195], v[20:23]
	v_mfma_f32_16x16x32_bf16 v[16:19], v[166:169], v[192:195], v[16:19]
	v_mfma_f32_16x16x32_bf16 v[4:7], v[158:161], v[200:203], v[4:7]
	v_mfma_f32_16x16x32_bf16 v[0:3], v[166:169], v[200:203], v[0:3]
	v_mfma_f32_16x16x32_bf16 v[52:55], v[162:165], v[180:183], v[52:55]
	v_mfma_f32_16x16x32_bf16 v[48:51], v[172:175], v[180:183], v[48:51]
	v_mfma_f32_16x16x32_bf16 v[36:39], v[162:165], v[188:191], v[36:39]
	v_mfma_f32_16x16x32_bf16 v[32:35], v[172:175], v[188:191], v[32:35]
	v_mfma_f32_16x16x32_bf16 v[20:23], v[162:165], v[196:199], v[20:23]
	v_mfma_f32_16x16x32_bf16 v[16:19], v[172:175], v[196:199], v[16:19]
	v_mfma_f32_16x16x32_bf16 v[4:7], v[162:165], v[204:207], v[4:7]
	v_mfma_f32_16x16x32_bf16 v[0:3], v[172:175], v[204:207], v[0:3]
	s_barrier
	s_add_i32 s38, 0, 0x18000
	s_add_i32 s39, 0, 0x1c000
	v_add_u32_e32 v154, s38, v97
	v_add_u32_e32 v171, s39, v97
	ds_read_b128 v[130:133], v154
	ds_read_b128 v[134:137], v154 offset:1024
	ds_read_b128 v[150:153], v154 offset:2048
	ds_read_b128 v[154:157], v154 offset:3072
	ds_read_b128 v[158:161], v171
	ds_read_b128 v[162:165], v171 offset:1024
	ds_read_b128 v[166:169], v171 offset:2048
	ds_read_b128 v[172:175], v171 offset:3072
	s_add_u32 s6, s6, s60
	s_addc_u32 s7, s7, s61
	s_mov_b32 m0, s41
	v_lshl_add_u64 v[228:229], s[6:7], 0, v[138:139]
	ds_read_b128 v[176:179], v170 offset:32768
	ds_read_b128 v[180:183], v170 offset:33792
	ds_read_b128 v[184:187], v170 offset:34816
	ds_read_b128 v[188:191], v170 offset:35840
	ds_read_b128 v[192:195], v170 offset:36864
	ds_read_b128 v[196:199], v170 offset:37888
	ds_read_b128 v[200:203], v170 offset:38912
	ds_read_b128 v[204:207], v170 offset:39936
	global_load_lds_dwordx4 v[228:229], off
	v_lshl_add_u64 v[228:229], s[6:7], 0, v[142:143]
	s_mov_b32 m0, s4
	s_nop 0
	global_load_lds_dwordx4 v[228:229], off
	s_waitcnt vmcnt(8)
	s_waitcnt lgkmcnt(0)
	s_barrier
	s_waitcnt lgkmcnt(0)
	v_mfma_f32_16x16x32_bf16 v[122:125], v[130:133], v[176:179], v[122:125]
	v_mfma_f32_16x16x32_bf16 v[126:129], v[150:153], v[176:179], v[126:129]
	v_mfma_f32_16x16x32_bf16 v[110:113], v[130:133], v[184:187], v[110:113]
	v_mfma_f32_16x16x32_bf16 v[106:109], v[150:153], v[184:187], v[106:109]
	v_mfma_f32_16x16x32_bf16 v[92:95], v[130:133], v[192:195], v[92:95]
	v_mfma_f32_16x16x32_bf16 v[88:91], v[150:153], v[192:195], v[88:91]
	v_mfma_f32_16x16x32_bf16 v[76:79], v[130:133], v[200:203], v[76:79]
	v_mfma_f32_16x16x32_bf16 v[72:75], v[150:153], v[200:203], v[72:75]
	v_mfma_f32_16x16x32_bf16 v[122:125], v[134:137], v[180:183], v[122:125]
	v_mfma_f32_16x16x32_bf16 v[126:129], v[154:157], v[180:183], v[126:129]
	v_mfma_f32_16x16x32_bf16 v[110:113], v[134:137], v[188:191], v[110:113]
	v_mfma_f32_16x16x32_bf16 v[106:109], v[154:157], v[188:191], v[106:109]
	v_mfma_f32_16x16x32_bf16 v[92:95], v[134:137], v[196:199], v[92:95]
	v_mfma_f32_16x16x32_bf16 v[88:91], v[154:157], v[196:199], v[88:91]
	v_mfma_f32_16x16x32_bf16 v[76:79], v[134:137], v[204:207], v[76:79]
	v_mfma_f32_16x16x32_bf16 v[72:75], v[154:157], v[204:207], v[72:75]
	v_mfma_f32_16x16x32_bf16 v[118:121], v[158:161], v[176:179], v[118:121]
	v_mfma_f32_16x16x32_bf16 v[114:117], v[166:169], v[176:179], v[114:117]
	v_mfma_f32_16x16x32_bf16 v[102:105], v[158:161], v[184:187], v[102:105]
	v_mfma_f32_16x16x32_bf16 v[98:101], v[166:169], v[184:187], v[98:101]
	v_mfma_f32_16x16x32_bf16 v[84:87], v[158:161], v[192:195], v[84:87]
	v_mfma_f32_16x16x32_bf16 v[80:83], v[166:169], v[192:195], v[80:83]
	v_mfma_f32_16x16x32_bf16 v[68:71], v[158:161], v[200:203], v[68:71]
	v_mfma_f32_16x16x32_bf16 v[64:67], v[166:169], v[200:203], v[64:67]
	v_mfma_f32_16x16x32_bf16 v[118:121], v[162:165], v[180:183], v[118:121]
	v_mfma_f32_16x16x32_bf16 v[114:117], v[172:175], v[180:183], v[114:117]
	v_mfma_f32_16x16x32_bf16 v[102:105], v[162:165], v[188:191], v[102:105]
	v_mfma_f32_16x16x32_bf16 v[98:101], v[172:175], v[188:191], v[98:101]
	v_mfma_f32_16x16x32_bf16 v[84:87], v[162:165], v[196:199], v[84:87]
	v_mfma_f32_16x16x32_bf16 v[80:83], v[172:175], v[196:199], v[80:83]
	v_mfma_f32_16x16x32_bf16 v[68:71], v[162:165], v[204:207], v[68:71]
	v_mfma_f32_16x16x32_bf16 v[64:67], v[172:175], v[204:207], v[64:67]
	s_barrier
; #define PG8_STAGE(bufoff, gbase, voff) do { _Pragma("unroll") for (int _i = 0; _i < 2; ++_i) \
;         __builtin_amdgcn_global_load_lds((const unsigned*)((const char*)(gbase) + (voff)[_i]), (PG8_LAS unsigned*)(lds + (bufoff) + ldsw + _i * 8192), 16, 0, 0); } while (0)
; #define PG8_LDA(dst, b, h) do { _Pragma("unroll") for (int m = 0; m < 4; ++m) _Pragma("unroll") for (int k = 0; k < 2; ++k) dst[m][k] = *(const PG8_LAS bf16x8*)(lds + PG8_SA(b, h) + aoff + m * 2048 + k * 1024); } while (0)
; #define PG8_MMA(ai, bj, At, Bt) do { __builtin_amdgcn_s_setprio(1); _Pragma("unroll") for (int m = 0; m < 4; ++m) _Pragma("unroll") for (int n = 0; n < 2; ++n) _Pragma("unroll") for (int k = 0; k < 2; ++k) \
;         acc[ai][bj][m][n] = __builtin_amdgcn_mfma_f32_16x16x32_bf16(Bt[n][k], At[m][k], acc[ai][bj][m][n], 0, 0, 0); __builtin_amdgcn_s_setprio(0); } while (0)
; #define PG8_WAIT_V(n) asm volatile("s_waitcnt vmcnt(" #n ")" ::: "memory")
; #define PG8_WAIT_L(n) asm volatile("s_waitcnt lgkmcnt(" #n ")" ::: "memory")
; #define PG8_BAR __builtin_amdgcn_s_barrier()
; #define PG8_SCHED __builtin_amdgcn_sched_barrier(0)
; template <class Epi>
; __device__ __forceinline__ void gemm_phase(PG8_LAS unsigned char* lds, const Gemm g, const StaticOrder& S, const Epi& E, const int wave_s) {
;     ...
;             PG8_LDA(At, 1, 1); PG8_STAGE(PG8_SB(1, 0), b3, voffB); PG8_STAGE(PG8_SB(1, 1), b3 + hstepB, voffB); PG8_STAGE(PG8_SA(1, 0), a3, voffA);
;             PG8_WAIT_V(8); PG8_WAIT_L(0); PG8_BAR; PG8_MMA(1, 0, At, B0); PG8_MMA(1, 1, At, B1); PG8_BAR; PG8_SCHED;
;         }
	s_add_i32 s6, s38, s12
	v_lshl_add_u64 v[208:209], v[208:209], 0, s[52:53]
	s_mov_b32 m0, s6
	ds_read_b128 v[176:179], v170 offset:49152
	ds_read_b128 v[180:183], v170 offset:50176
	ds_read_b128 v[184:187], v170 offset:51200
	ds_read_b128 v[188:191], v170 offset:52224
	ds_read_b128 v[192:195], v170 offset:53248
	ds_read_b128 v[196:199], v170 offset:54272
	ds_read_b128 v[200:203], v170 offset:55296
	ds_read_b128 v[204:207], v170 offset:56320
	global_load_lds_dwordx4 v[208:209], off
	v_lshl_add_u64 v[208:209], v[218:219], 0, s[52:53]
	s_add_i32 m0, s6, 0x2000
	s_add_i32 s6, s39, s12
	global_load_lds_dwordx4 v[208:209], off
	v_lshl_add_u64 v[208:209], v[220:221], 0, s[52:53]
	s_mov_b32 m0, s6
	s_nop 0
	global_load_lds_dwordx4 v[208:209], off
	v_lshl_add_u64 v[208:209], v[222:223], 0, s[52:53]
	s_add_i32 m0, s6, 0x2000
	s_nop 0
	global_load_lds_dwordx4 v[208:209], off
	v_lshl_add_u64 v[208:209], v[224:225], 0, s[52:53]
	s_mov_b32 m0, s10
	s_nop 0
	global_load_lds_dwordx4 v[208:209], off
	v_lshl_add_u64 v[208:209], v[226:227], 0, s[52:53]
	s_mov_b32 m0, s11
	s_nop 0
	global_load_lds_dwordx4 v[208:209], off
	s_waitcnt vmcnt(8)
	s_waitcnt lgkmcnt(0)
	s_barrier
	s_waitcnt lgkmcnt(0)
	v_mfma_f32_16x16x32_bf16 v[60:63], v[130:133], v[176:179], v[60:63]
	v_mfma_f32_16x16x32_bf16 v[56:59], v[150:153], v[176:179], v[56:59]
	s_add_u32 s44, s44, 0x100
	s_addc_u32 s45, s45, 0
	s_add_u32 s9, s9, 0x100
	s_addc_u32 s25, s25, 0
	s_mov_b32 s6, s36
	s_cmp_ge_i32 s36, s68
	v_mfma_f32_16x16x32_bf16 v[44:47], v[130:133], v[184:187], v[44:47]
	v_mfma_f32_16x16x32_bf16 v[40:43], v[150:153], v[184:187], v[40:43]
	v_mfma_f32_16x16x32_bf16 v[28:31], v[130:133], v[192:195], v[28:31]
	v_mfma_f32_16x16x32_bf16 v[24:27], v[150:153], v[192:195], v[24:27]
	v_mfma_f32_16x16x32_bf16 v[12:15], v[130:133], v[200:203], v[12:15]
	v_mfma_f32_16x16x32_bf16 v[8:11], v[150:153], v[200:203], v[8:11]
	v_mfma_f32_16x16x32_bf16 v[60:63], v[134:137], v[180:183], v[60:63]
	v_mfma_f32_16x16x32_bf16 v[56:59], v[154:157], v[180:183], v[56:59]
	v_mfma_f32_16x16x32_bf16 v[44:47], v[134:137], v[188:191], v[44:47]
	v_mfma_f32_16x16x32_bf16 v[40:43], v[154:157], v[188:191], v[40:43]
	v_mfma_f32_16x16x32_bf16 v[28:31], v[134:137], v[196:199], v[28:31]
	v_mfma_f32_16x16x32_bf16 v[24:27], v[154:157], v[196:199], v[24:27]
	v_mfma_f32_16x16x32_bf16 v[12:15], v[134:137], v[204:207], v[12:15]
	v_mfma_f32_16x16x32_bf16 v[8:11], v[154:157], v[204:207], v[8:11]
	v_mfma_f32_16x16x32_bf16 v[52:55], v[158:161], v[176:179], v[52:55]
	v_mfma_f32_16x16x32_bf16 v[48:51], v[166:169], v[176:179], v[48:51]
	v_mfma_f32_16x16x32_bf16 v[36:39], v[158:161], v[184:187], v[36:39]
	v_mfma_f32_16x16x32_bf16 v[32:35], v[166:169], v[184:187], v[32:35]
	v_mfma_f32_16x16x32_bf16 v[20:23], v[158:161], v[192:195], v[20:23]
	v_mfma_f32_16x16x32_bf16 v[16:19], v[166:169], v[192:195], v[16:19]
	v_mfma_f32_16x16x32_bf16 v[4:7], v[158:161], v[200:203], v[4:7]
	v_mfma_f32_16x16x32_bf16 v[0:3], v[166:169], v[200:203], v[0:3]
	v_mfma_f32_16x16x32_bf16 v[52:55], v[162:165], v[180:183], v[52:55]
	v_mfma_f32_16x16x32_bf16 v[48:51], v[172:175], v[180:183], v[48:51]
	v_mfma_f32_16x16x32_bf16 v[36:39], v[162:165], v[188:191], v[36:39]
	v_mfma_f32_16x16x32_bf16 v[32:35], v[172:175], v[188:191], v[32:35]
	v_mfma_f32_16x16x32_bf16 v[20:23], v[162:165], v[196:199], v[20:23]
	v_mfma_f32_16x16x32_bf16 v[16:19], v[172:175], v[196:199], v[16:19]
	v_mfma_f32_16x16x32_bf16 v[4:7], v[162:165], v[204:207], v[4:7]
	v_mfma_f32_16x16x32_bf16 v[0:3], v[172:175], v[204:207], v[0:3]
	s_barrier
	s_cbranch_scc0 .LBB0_336
	s_setprio 0

; #define PG8_STAGE(bufoff, gbase, voff) do { _Pragma("unroll") for (int _i = 0; _i < 2; ++_i) \
;         __builtin_amdgcn_global_load_lds((const unsigned*)((const char*)(gbase) + (voff)[_i]), (PG8_LAS unsigned*)(lds + (bufoff) + ldsw + _i * 8192), 16, 0, 0); } while (0)
; #define PG8_LDA(dst, b, h) do { _Pragma("unroll") for (int m = 0; m < 4; ++m) _Pragma("unroll") for (int k = 0; k < 2; ++k) dst[m][k] = *(const PG8_LAS bf16x8*)(lds + PG8_SA(b, h) + aoff + m * 2048 + k * 1024); } while (0)
; #define PG8_LDB(dst, b, h) do { _Pragma("unroll") for (int n = 0; n < 2; ++n) _Pragma("unroll") for (int k = 0; k < 2; ++k) dst[n][k] = *(const PG8_LAS bf16x8*)(lds + PG8_SB(b, h) + boff + n * 2048 + k * 1024); } while (0)
; #define PG8_MMA(ai, bj, At, Bt) do { __builtin_amdgcn_s_setprio(1); _Pragma("unroll") for (int m = 0; m < 4; ++m) _Pragma("unroll") for (int n = 0; n < 2; ++n) _Pragma("unroll") for (int k = 0; k < 2; ++k) \
;         acc[ai][bj][m][n] = __builtin_amdgcn_mfma_f32_16x16x32_bf16(Bt[n][k], At[m][k], acc[ai][bj][m][n], 0, 0, 0); __builtin_amdgcn_s_setprio(0); } while (0)
; #define PG8_WAIT_V(n) asm volatile("s_waitcnt vmcnt(" #n ")" ::: "memory")
; #define PG8_WAIT_L(n) asm volatile("s_waitcnt lgkmcnt(" #n ")" ::: "memory")
; #define PG8_BAR __builtin_amdgcn_s_barrier()
; #define PG8_SCHED __builtin_amdgcn_sched_barrier(0)
; template <class Epi>
; __device__ __forceinline__ void gemm_phase(PG8_LAS unsigned char* lds, const Gemm g, const StaticOrder& S, const Epi& E, const int wave_s) {
;     ...
;             const bool last = (t == nt - 2);
;             const char* a1 = cA + (size_t)(t + 1) * kstep;
;             const char* a2 = last ? nA : cA + (size_t)(t + 2) * kstep; const char* b2 = last ? nB : cB + (size_t)(t + 2) * kstep;
;             const char* a3 = a2 + kstep; const char* b3 = b2 + kstep;
;             PG8_LDB(B0, 0, 0); PG8_LDB(B1, 0, 1); PG8_SCHED; PG8_LDA(At, 0, 0); PG8_STAGE(PG8_SA(1, 1), a1 + hstepA, voffA);
;             PG8_WAIT_V(8); PG8_WAIT_L(0); PG8_BAR; PG8_MMA(0, 0, At, B0); PG8_MMA(0, 1, At, B1); PG8_BAR; PG8_SCHED;
;             PG8_LDA(At, 0, 1); PG8_STAGE(PG8_SB(0, 0), b2, voffB); PG8_STAGE(PG8_SB(0, 1), b2 + hstepB, voffB); PG8_STAGE(PG8_SA(0, 0), a2, voffA);
;             PG8_WAIT_V(8); PG8_WAIT_L(0); PG8_BAR; PG8_MMA(1, 0, At, B0); PG8_MMA(1, 1, At, B1); PG8_BAR; PG8_SCHED;
.Lg2_prio_done:
.LBB0_459:
	s_add_i32 s16, 0, 0x10000
	v_add_u32_e32 v154, s16, v97
	ds_read_b128 v[130:133], v154
	ds_read_b128 v[146:149], v154 offset:1024
	ds_read_b128 v[150:153], v154 offset:2048
	ds_read_b128 v[158:161], v154 offset:3072
	s_add_i32 s12, s6, 2
	s_add_u32 s13, s44, 0x80
	s_addc_u32 s7, s45, 0
	s_cmp_eq_u32 s36, s6
	s_cselect_b32 s7, s71, s7
	s_cselect_b32 s6, s70, s13
	s_cselect_b32 s39, s87, s9
	s_cselect_b32 s38, s86, s8
	s_add_i32 s13, 0, 0x14000
	v_add_u32_e32 v154, s13, v97
	ds_read_b128 v[162:165], v154
	ds_read_b128 v[166:169], v154 offset:1024
	ds_read_b128 v[170:173], v154 offset:2048
	ds_read_b128 v[174:177], v154 offset:3072
	v_lshl_add_u64 v[154:155], s[44:45], 0, v[142:143]
	s_add_i32 m0, s40, 0xc000
	ds_read_b128 v[178:181], v156
	ds_read_b128 v[182:185], v156 offset:1024
	ds_read_b128 v[186:189], v156 offset:2048
	ds_read_b128 v[190:193], v156 offset:3072
	ds_read_b128 v[194:197], v156 offset:4096
	ds_read_b128 v[198:201], v156 offset:5120
	ds_read_b128 v[202:205], v156 offset:6144
	ds_read_b128 v[206:209], v156 offset:7168
	global_load_lds_dwordx4 v[154:155], off
	v_lshl_add_u64 v[154:155], s[44:45], 0, v[144:145]
	s_add_i32 m0, s40, 0xe000
	s_nop 0
	global_load_lds_dwordx4 v[154:155], off
	s_waitcnt vmcnt(8)
	s_waitcnt lgkmcnt(0)
	s_barrier
	s_waitcnt lgkmcnt(0)
	v_mfma_f32_16x16x32_bf16 v[126:129], v[130:133], v[178:181], v[126:129]
	v_mfma_f32_16x16x32_bf16 v[122:125], v[150:153], v[178:181], v[122:125]
	v_mfma_f32_16x16x32_bf16 v[110:113], v[130:133], v[186:189], v[110:113]
	v_mfma_f32_16x16x32_bf16 v[106:109], v[150:153], v[186:189], v[106:109]
	v_mfma_f32_16x16x32_bf16 v[92:95], v[130:133], v[194:197], v[92:95]
	v_mfma_f32_16x16x32_bf16 v[88:91], v[150:153], v[194:197], v[88:91]
	v_mfma_f32_16x16x32_bf16 v[76:79], v[130:133], v[202:205], v[76:79]
	v_mfma_f32_16x16x32_bf16 v[72:75], v[150:153], v[202:205], v[72:75]
	v_mfma_f32_16x16x32_bf16 v[126:129], v[146:149], v[182:185], v[126:129]
	v_mfma_f32_16x16x32_bf16 v[122:125], v[158:161], v[182:185], v[122:125]
	v_mfma_f32_16x16x32_bf16 v[110:113], v[146:149], v[190:193], v[110:113]
	v_mfma_f32_16x16x32_bf16 v[106:109], v[158:161], v[190:193], v[106:109]
	v_mfma_f32_16x16x32_bf16 v[92:95], v[146:149], v[198:201], v[92:95]
	v_mfma_f32_16x16x32_bf16 v[88:91], v[158:161], v[198:201], v[88:91]
	v_mfma_f32_16x16x32_bf16 v[76:79], v[146:149], v[206:209], v[76:79]
	v_mfma_f32_16x16x32_bf16 v[72:75], v[158:161], v[206:209], v[72:75]
	v_mfma_f32_16x16x32_bf16 v[118:121], v[162:165], v[178:181], v[118:121]
	v_mfma_f32_16x16x32_bf16 v[114:117], v[170:173], v[178:181], v[114:117]
	v_mfma_f32_16x16x32_bf16 v[102:105], v[162:165], v[186:189], v[102:105]
	v_mfma_f32_16x16x32_bf16 v[98:101], v[170:173], v[186:189], v[98:101]
	v_mfma_f32_16x16x32_bf16 v[84:87], v[162:165], v[194:197], v[84:87]
	v_mfma_f32_16x16x32_bf16 v[80:83], v[170:173], v[194:197], v[80:83]
	v_mfma_f32_16x16x32_bf16 v[68:71], v[162:165], v[202:205], v[68:71]
	v_mfma_f32_16x16x32_bf16 v[64:67], v[170:173], v[202:205], v[64:67]
	v_mfma_f32_16x16x32_bf16 v[118:121], v[166:169], v[182:185], v[118:121]
	v_mfma_f32_16x16x32_bf16 v[114:117], v[174:177], v[182:185], v[114:117]
	v_mfma_f32_16x16x32_bf16 v[102:105], v[166:169], v[190:193], v[102:105]
	v_mfma_f32_16x16x32_bf16 v[98:101], v[174:177], v[190:193], v[98:101]
	v_mfma_f32_16x16x32_bf16 v[84:87], v[166:169], v[198:201], v[84:87]
	v_mfma_f32_16x16x32_bf16 v[80:83], v[174:177], v[198:201], v[80:83]
	v_mfma_f32_16x16x32_bf16 v[68:71], v[166:169], v[206:209], v[68:71]
	v_mfma_f32_16x16x32_bf16 v[64:67], v[174:177], v[206:209], v[64:67]
	s_barrier
	s_add_i32 s16, s16, s37
	v_lshl_add_u64 v[154:155], s[38:39], 0, v[136:137]
	s_mov_b32 m0, s16
	ds_read_b128 v[178:181], v156 offset:16384
	ds_read_b128 v[182:185], v156 offset:17408
	ds_read_b128 v[186:189], v156 offset:18432
	ds_read_b128 v[190:193], v156 offset:19456
	ds_read_b128 v[194:197], v156 offset:20480
	ds_read_b128 v[198:201], v156 offset:21504
	ds_read_b128 v[202:205], v156 offset:22528
	ds_read_b128 v[206:209], v156 offset:23552
	global_load_lds_dwordx4 v[154:155], off
	s_add_i32 m0, s16, 0x2000
	v_lshl_add_u64 v[218:219], s[38:39], 0, v[140:141]
	s_add_u32 s38, s38, s50
	s_addc_u32 s39, s39, s51
	s_add_i32 s13, s13, s37
	global_load_lds_dwordx4 v[218:219], off
	v_lshl_add_u64 v[220:221], s[38:39], 0, v[136:137]
	s_mov_b32 m0, s13
	v_lshl_add_u64 v[222:223], s[38:39], 0, v[140:141]
	global_load_lds_dwordx4 v[220:221], off
	s_add_i32 m0, s13, 0x2000
	v_lshl_add_u64 v[224:225], s[6:7], 0, v[134:135]
	global_load_lds_dwordx4 v[222:223], off
	s_mov_b32 m0, s40
	v_lshl_add_u64 v[226:227], s[6:7], 0, v[138:139]
	global_load_lds_dwordx4 v[224:225], off
	s_mov_b32 m0, s41
	s_nop 0
	global_load_lds_dwordx4 v[226:227], off
	s_waitcnt vmcnt(8)
	s_waitcnt lgkmcnt(0)
	s_barrier
; #define PG8_STAGE(bufoff, gbase, voff) do { _Pragma("unroll") for (int _i = 0; _i < 2; ++_i) \
;         __builtin_amdgcn_global_load_lds((const unsigned*)((const char*)(gbase) + (voff)[_i]), (PG8_LAS unsigned*)(lds + (bufoff) + ldsw + _i * 8192), 16, 0, 0); } while (0)
; #define PG8_LDA(dst, b, h) do { _Pragma("unroll") for (int m = 0; m < 4; ++m) _Pragma("unroll") for (int k = 0; k < 2; ++k) dst[m][k] = *(const PG8_LAS bf16x8*)(lds + PG8_SA(b, h) + aoff + m * 2048 + k * 1024); } while (0)
; #define PG8_LDB(dst, b, h) do { _Pragma("unroll") for (int n = 0; n < 2; ++n) _Pragma("unroll") for (int k = 0; k < 2; ++k) dst[n][k] = *(const PG8_LAS bf16x8*)(lds + PG8_SB(b, h) + boff + n * 2048 + k * 1024); } while (0)
; #define PG8_MMA(ai, bj, At, Bt) do { __builtin_amdgcn_s_setprio(1); _Pragma("unroll") for (int m = 0; m < 4; ++m) _Pragma("unroll") for (int n = 0; n < 2; ++n) _Pragma("unroll") for (int k = 0; k < 2; ++k) \
;         acc[ai][bj][m][n] = __builtin_amdgcn_mfma_f32_16x16x32_bf16(Bt[n][k], At[m][k], acc[ai][bj][m][n], 0, 0, 0); __builtin_amdgcn_s_setprio(0); } while (0)
; #define PG8_WAIT_V(n) asm volatile("s_waitcnt vmcnt(" #n ")" ::: "memory")
; #define PG8_WAIT_L(n) asm volatile("s_waitcnt lgkmcnt(" #n ")" ::: "memory")
; #define PG8_BAR __builtin_amdgcn_s_barrier()
; #define PG8_SCHED __builtin_amdgcn_sched_barrier(0)
; template <class Epi>
; __device__ __forceinline__ void gemm_phase(PG8_LAS unsigned char* lds, const Gemm g, const StaticOrder& S, const Epi& E, const int wave_s) {
;     ...
;             PG8_WAIT_V(8); PG8_WAIT_L(0); PG8_BAR; PG8_MMA(1, 0, At, B0); PG8_MMA(1, 1, At, B1); PG8_BAR; PG8_SCHED;
;             PG8_LDB(B0, 1, 0); PG8_LDB(B1, 1, 1); PG8_SCHED; PG8_LDA(At, 1, 0); PG8_STAGE(PG8_SA(0, 1), a2 + hstepA, voffA);
;             PG8_WAIT_V(8); PG8_WAIT_L(0); PG8_BAR; PG8_MMA(0, 0, At, B0); PG8_MMA(0, 1, At, B1); PG8_BAR; PG8_SCHED;
	s_waitcnt lgkmcnt(0)
	v_mfma_f32_16x16x32_bf16 v[60:63], v[130:133], v[178:181], v[60:63]
	v_mfma_f32_16x16x32_bf16 v[56:59], v[150:153], v[178:181], v[56:59]
	v_mfma_f32_16x16x32_bf16 v[44:47], v[130:133], v[186:189], v[44:47]
	v_mfma_f32_16x16x32_bf16 v[40:43], v[150:153], v[186:189], v[40:43]
	v_mfma_f32_16x16x32_bf16 v[28:31], v[130:133], v[194:197], v[28:31]
	v_mfma_f32_16x16x32_bf16 v[24:27], v[150:153], v[194:197], v[24:27]
	v_mfma_f32_16x16x32_bf16 v[12:15], v[130:133], v[202:205], v[12:15]
	v_mfma_f32_16x16x32_bf16 v[8:11], v[150:153], v[202:205], v[8:11]
	v_mfma_f32_16x16x32_bf16 v[60:63], v[146:149], v[182:185], v[60:63]
	v_mfma_f32_16x16x32_bf16 v[56:59], v[158:161], v[182:185], v[56:59]
	v_mfma_f32_16x16x32_bf16 v[44:47], v[146:149], v[190:193], v[44:47]
	v_mfma_f32_16x16x32_bf16 v[40:43], v[158:161], v[190:193], v[40:43]
	v_mfma_f32_16x16x32_bf16 v[28:31], v[146:149], v[198:201], v[28:31]
	v_mfma_f32_16x16x32_bf16 v[24:27], v[158:161], v[198:201], v[24:27]
	v_mfma_f32_16x16x32_bf16 v[12:15], v[146:149], v[206:209], v[12:15]
	v_mfma_f32_16x16x32_bf16 v[8:11], v[158:161], v[206:209], v[8:11]
	v_mfma_f32_16x16x32_bf16 v[52:55], v[162:165], v[178:181], v[52:55]
	v_mfma_f32_16x16x32_bf16 v[48:51], v[170:173], v[178:181], v[48:51]
	v_mfma_f32_16x16x32_bf16 v[36:39], v[162:165], v[186:189], v[36:39]
	v_mfma_f32_16x16x32_bf16 v[32:35], v[170:173], v[186:189], v[32:35]
	v_mfma_f32_16x16x32_bf16 v[20:23], v[162:165], v[194:197], v[20:23]
	v_mfma_f32_16x16x32_bf16 v[16:19], v[170:173], v[194:197], v[16:19]
	v_mfma_f32_16x16x32_bf16 v[4:7], v[162:165], v[202:205], v[4:7]
	v_mfma_f32_16x16x32_bf16 v[0:3], v[170:173], v[202:205], v[0:3]
	v_mfma_f32_16x16x32_bf16 v[52:55], v[166:169], v[182:185], v[52:55]
	v_mfma_f32_16x16x32_bf16 v[48:51], v[174:177], v[182:185], v[48:51]
	v_mfma_f32_16x16x32_bf16 v[36:39], v[166:169], v[190:193], v[36:39]
	v_mfma_f32_16x16x32_bf16 v[32:35], v[174:177], v[190:193], v[32:35]
	v_mfma_f32_16x16x32_bf16 v[20:23], v[166:169], v[198:201], v[20:23]
	v_mfma_f32_16x16x32_bf16 v[16:19], v[174:177], v[198:201], v[16:19]
	v_mfma_f32_16x16x32_bf16 v[4:7], v[166:169], v[206:209], v[4:7]
	v_mfma_f32_16x16x32_bf16 v[0:3], v[174:177], v[206:209], v[0:3]
	s_barrier
	s_add_i32 s13, 0, 0x18000
	v_add_u32_e32 v157, s13, v97
	s_add_i32 s16, 0, 0x1c000
	ds_read_b128 v[130:133], v157
	ds_read_b128 v[146:149], v157 offset:1024
	ds_read_b128 v[150:153], v157 offset:2048
	ds_read_b128 v[158:161], v157 offset:3072
	v_add_u32_e32 v157, s16, v97
	ds_read_b128 v[162:165], v157
	ds_read_b128 v[166:169], v157 offset:1024
	ds_read_b128 v[170:173], v157 offset:2048
	ds_read_b128 v[174:177], v157 offset:3072
	s_add_u32 s6, s6, s48
	s_addc_u32 s7, s7, s49
	s_mov_b32 m0, s92
	v_lshl_add_u64 v[228:229], s[6:7], 0, v[134:135]
	ds_read_b128 v[178:181], v156 offset:32768
	ds_read_b128 v[182:185], v156 offset:33792
	ds_read_b128 v[186:189], v156 offset:34816
	ds_read_b128 v[190:193], v156 offset:35840
	ds_read_b128 v[194:197], v156 offset:36864
	ds_read_b128 v[198:201], v156 offset:37888
	ds_read_b128 v[202:205], v156 offset:38912
	ds_read_b128 v[206:209], v156 offset:39936
	global_load_lds_dwordx4 v[228:229], off
	v_lshl_add_u64 v[228:229], s[6:7], 0, v[138:139]
	s_mov_b32 m0, s93
	s_nop 0
	global_load_lds_dwordx4 v[228:229], off
	s_waitcnt vmcnt(8)
	s_waitcnt lgkmcnt(0)
	s_barrier
	s_waitcnt lgkmcnt(0)
	v_mfma_f32_16x16x32_bf16 v[126:129], v[130:133], v[178:181], v[126:129]
	v_mfma_f32_16x16x32_bf16 v[122:125], v[150:153], v[178:181], v[122:125]
	v_mfma_f32_16x16x32_bf16 v[110:113], v[130:133], v[186:189], v[110:113]
	v_mfma_f32_16x16x32_bf16 v[106:109], v[150:153], v[186:189], v[106:109]
	v_mfma_f32_16x16x32_bf16 v[92:95], v[130:133], v[194:197], v[92:95]
	v_mfma_f32_16x16x32_bf16 v[88:91], v[150:153], v[194:197], v[88:91]
	v_mfma_f32_16x16x32_bf16 v[76:79], v[130:133], v[202:205], v[76:79]
	v_mfma_f32_16x16x32_bf16 v[72:75], v[150:153], v[202:205], v[72:75]
	v_mfma_f32_16x16x32_bf16 v[126:129], v[146:149], v[182:185], v[126:129]
	v_mfma_f32_16x16x32_bf16 v[122:125], v[158:161], v[182:185], v[122:125]
	v_mfma_f32_16x16x32_bf16 v[110:113], v[146:149], v[190:193], v[110:113]
	v_mfma_f32_16x16x32_bf16 v[106:109], v[158:161], v[190:193], v[106:109]
	v_mfma_f32_16x16x32_bf16 v[92:95], v[146:149], v[198:201], v[92:95]
	v_mfma_f32_16x16x32_bf16 v[88:91], v[158:161], v[198:201], v[88:91]
	v_mfma_f32_16x16x32_bf16 v[76:79], v[146:149], v[206:209], v[76:79]
	v_mfma_f32_16x16x32_bf16 v[72:75], v[158:161], v[206:209], v[72:75]
	v_mfma_f32_16x16x32_bf16 v[118:121], v[162:165], v[178:181], v[118:121]
	v_mfma_f32_16x16x32_bf16 v[114:117], v[170:173], v[178:181], v[114:117]
	v_mfma_f32_16x16x32_bf16 v[102:105], v[162:165], v[186:189], v[102:105]
	v_mfma_f32_16x16x32_bf16 v[98:101], v[170:173], v[186:189], v[98:101]
	v_mfma_f32_16x16x32_bf16 v[84:87], v[162:165], v[194:197], v[84:87]
	v_mfma_f32_16x16x32_bf16 v[80:83], v[170:173], v[194:197], v[80:83]
	v_mfma_f32_16x16x32_bf16 v[68:71], v[162:165], v[202:205], v[68:71]
	v_mfma_f32_16x16x32_bf16 v[64:67], v[170:173], v[202:205], v[64:67]
	v_mfma_f32_16x16x32_bf16 v[118:121], v[166:169], v[182:185], v[118:121]
	v_mfma_f32_16x16x32_bf16 v[114:117], v[174:177], v[182:185], v[114:117]
	v_mfma_f32_16x16x32_bf16 v[102:105], v[166:169], v[190:193], v[102:105]
	v_mfma_f32_16x16x32_bf16 v[98:101], v[174:177], v[190:193], v[98:101]
	v_mfma_f32_16x16x32_bf16 v[84:87], v[166:169], v[198:201], v[84:87]
	v_mfma_f32_16x16x32_bf16 v[80:83], v[174:177], v[198:201], v[80:83]
	v_mfma_f32_16x16x32_bf16 v[68:71], v[166:169], v[206:209], v[68:71]
	v_mfma_f32_16x16x32_bf16 v[64:67], v[174:177], v[206:209], v[64:67]
	s_barrier
; #define PG8_STAGE(bufoff, gbase, voff) do { _Pragma("unroll") for (int _i = 0; _i < 2; ++_i) \
;         __builtin_amdgcn_global_load_lds((const unsigned*)((const char*)(gbase) + (voff)[_i]), (PG8_LAS unsigned*)(lds + (bufoff) + ldsw + _i * 8192), 16, 0, 0); } while (0)
; #define PG8_LDA(dst, b, h) do { _Pragma("unroll") for (int m = 0; m < 4; ++m) _Pragma("unroll") for (int k = 0; k < 2; ++k) dst[m][k] = *(const PG8_LAS bf16x8*)(lds + PG8_SA(b, h) + aoff + m * 2048 + k * 1024); } while (0)
; #define PG8_MMA(ai, bj, At, Bt) do { __builtin_amdgcn_s_setprio(1); _Pragma("unroll") for (int m = 0; m < 4; ++m) _Pragma("unroll") for (int n = 0; n < 2; ++n) _Pragma("unroll") for (int k = 0; k < 2; ++k) \
;         acc[ai][bj][m][n] = __builtin_amdgcn_mfma_f32_16x16x32_bf16(Bt[n][k], At[m][k], acc[ai][bj][m][n], 0, 0, 0); __builtin_amdgcn_s_setprio(0); } while (0)
; #define PG8_WAIT_V(n) asm volatile("s_waitcnt vmcnt(" #n ")" ::: "memory")
; #define PG8_WAIT_L(n) asm volatile("s_waitcnt lgkmcnt(" #n ")" ::: "memory")
; #define PG8_BAR __builtin_amdgcn_s_barrier()
; #define PG8_SCHED __builtin_amdgcn_sched_barrier(0)
; template <class Epi>
; __device__ __forceinline__ void gemm_phase(PG8_LAS unsigned char* lds, const Gemm g, const StaticOrder& S, const Epi& E, const int wave_s) {
;     ...
;             PG8_LDA(At, 1, 1); PG8_STAGE(PG8_SB(1, 0), b3, voffB); PG8_STAGE(PG8_SB(1, 1), b3 + hstepB, voffB); PG8_STAGE(PG8_SA(1, 0), a3, voffA);
;             PG8_WAIT_V(8); PG8_WAIT_L(0); PG8_BAR; PG8_MMA(1, 0, At, B0); PG8_MMA(1, 1, At, B1); PG8_BAR; PG8_SCHED;
;         }
	s_add_i32 s6, s13, s37
	v_lshl_add_u64 v[154:155], v[154:155], 0, s[52:53]
	s_mov_b32 m0, s6
	ds_read_b128 v[178:181], v156 offset:49152
	ds_read_b128 v[182:185], v156 offset:50176
	ds_read_b128 v[186:189], v156 offset:51200
	ds_read_b128 v[190:193], v156 offset:52224
	ds_read_b128 v[194:197], v156 offset:53248
	ds_read_b128 v[198:201], v156 offset:54272
	ds_read_b128 v[202:205], v156 offset:55296
	ds_read_b128 v[206:209], v156 offset:56320
	global_load_lds_dwordx4 v[154:155], off
	v_lshl_add_u64 v[154:155], v[218:219], 0, s[52:53]
	s_add_i32 m0, s6, 0x2000
	s_add_i32 s6, s16, s37
	global_load_lds_dwordx4 v[154:155], off
	v_lshl_add_u64 v[154:155], v[220:221], 0, s[52:53]
	s_mov_b32 m0, s6
	s_nop 0
	global_load_lds_dwordx4 v[154:155], off
	v_lshl_add_u64 v[154:155], v[222:223], 0, s[52:53]
	s_add_i32 m0, s6, 0x2000
	s_nop 0
	global_load_lds_dwordx4 v[154:155], off
	v_lshl_add_u64 v[154:155], v[224:225], 0, s[52:53]
	s_mov_b32 m0, s64
	s_nop 0
	global_load_lds_dwordx4 v[154:155], off
	v_lshl_add_u64 v[154:155], v[226:227], 0, s[52:53]
	s_mov_b32 m0, s65
	s_nop 0
	global_load_lds_dwordx4 v[154:155], off
	s_waitcnt vmcnt(8)
	s_waitcnt lgkmcnt(0)
	s_barrier
	s_waitcnt lgkmcnt(0)
	v_mfma_f32_16x16x32_bf16 v[60:63], v[130:133], v[178:181], v[60:63]
	v_mfma_f32_16x16x32_bf16 v[56:59], v[150:153], v[178:181], v[56:59]
	s_add_u32 s44, s44, 0x100
	s_addc_u32 s45, s45, 0
	s_add_u32 s8, s8, 0x100
	s_addc_u32 s9, s9, 0
	s_mov_b32 s6, s12
	s_cmp_ge_i32 s12, s4
	v_mfma_f32_16x16x32_bf16 v[44:47], v[130:133], v[186:189], v[44:47]
	v_mfma_f32_16x16x32_bf16 v[40:43], v[150:153], v[186:189], v[40:43]
	v_mfma_f32_16x16x32_bf16 v[28:31], v[130:133], v[194:197], v[28:31]
	v_mfma_f32_16x16x32_bf16 v[24:27], v[150:153], v[194:197], v[24:27]
	v_mfma_f32_16x16x32_bf16 v[12:15], v[130:133], v[202:205], v[12:15]
	v_mfma_f32_16x16x32_bf16 v[8:11], v[150:153], v[202:205], v[8:11]
	v_mfma_f32_16x16x32_bf16 v[60:63], v[146:149], v[182:185], v[60:63]
	v_mfma_f32_16x16x32_bf16 v[56:59], v[158:161], v[182:185], v[56:59]
	v_mfma_f32_16x16x32_bf16 v[44:47], v[146:149], v[190:193], v[44:47]
	v_mfma_f32_16x16x32_bf16 v[40:43], v[158:161], v[190:193], v[40:43]
	v_mfma_f32_16x16x32_bf16 v[28:31], v[146:149], v[198:201], v[28:31]
	v_mfma_f32_16x16x32_bf16 v[24:27], v[158:161], v[198:201], v[24:27]
	v_mfma_f32_16x16x32_bf16 v[12:15], v[146:149], v[206:209], v[12:15]
	v_mfma_f32_16x16x32_bf16 v[8:11], v[158:161], v[206:209], v[8:11]
	v_mfma_f32_16x16x32_bf16 v[52:55], v[162:165], v[178:181], v[52:55]
	v_mfma_f32_16x16x32_bf16 v[48:51], v[170:173], v[178:181], v[48:51]
	v_mfma_f32_16x16x32_bf16 v[36:39], v[162:165], v[186:189], v[36:39]
	v_mfma_f32_16x16x32_bf16 v[32:35], v[170:173], v[186:189], v[32:35]
	v_mfma_f32_16x16x32_bf16 v[20:23], v[162:165], v[194:197], v[20:23]
	v_mfma_f32_16x16x32_bf16 v[16:19], v[170:173], v[194:197], v[16:19]
	v_mfma_f32_16x16x32_bf16 v[4:7], v[162:165], v[202:205], v[4:7]
	v_mfma_f32_16x16x32_bf16 v[0:3], v[170:173], v[202:205], v[0:3]
	v_mfma_f32_16x16x32_bf16 v[52:55], v[166:169], v[182:185], v[52:55]
	v_mfma_f32_16x16x32_bf16 v[48:51], v[174:177], v[182:185], v[48:51]
	v_mfma_f32_16x16x32_bf16 v[36:39], v[166:169], v[190:193], v[36:39]
	v_mfma_f32_16x16x32_bf16 v[32:35], v[174:177], v[190:193], v[32:35]
	v_mfma_f32_16x16x32_bf16 v[20:23], v[166:169], v[198:201], v[20:23]
	v_mfma_f32_16x16x32_bf16 v[16:19], v[174:177], v[198:201], v[16:19]
	v_mfma_f32_16x16x32_bf16 v[4:7], v[166:169], v[206:209], v[4:7]
	v_mfma_f32_16x16x32_bf16 v[0:3], v[174:177], v[206:209], v[0:3]
	s_barrier
	s_cbranch_scc0 .LBB0_459
	s_setprio 0
	v_readlane_b32 s38, v255, 5
	v_readlane_b32 s39, v255, 6

; #define PG8_STAGE(bufoff, gbase, voff) do { _Pragma("unroll") for (int _i = 0; _i < 2; ++_i) \
;         __builtin_amdgcn_global_load_lds((const unsigned*)((const char*)(gbase) + (voff)[_i]), (PG8_LAS unsigned*)(lds + (bufoff) + ldsw + _i * 8192), 16, 0, 0); } while (0)
; #define PG8_LDA(dst, b, h) do { _Pragma("unroll") for (int m = 0; m < 4; ++m) _Pragma("unroll") for (int k = 0; k < 2; ++k) dst[m][k] = *(const PG8_LAS bf16x8*)(lds + PG8_SA(b, h) + aoff + m * 2048 + k * 1024); } while (0)
; #define PG8_LDB(dst, b, h) do { _Pragma("unroll") for (int n = 0; n < 2; ++n) _Pragma("unroll") for (int k = 0; k < 2; ++k) dst[n][k] = *(const PG8_LAS bf16x8*)(lds + PG8_SB(b, h) + boff + n * 2048 + k * 1024); } while (0)
; #define PG8_MMA(ai, bj, At, Bt) do { __builtin_amdgcn_s_setprio(1); _Pragma("unroll") for (int m = 0; m < 4; ++m) _Pragma("unroll") for (int n = 0; n < 2; ++n) _Pragma("unroll") for (int k = 0; k < 2; ++k) \
;         acc[ai][bj][m][n] = __builtin_amdgcn_mfma_f32_16x16x32_bf16(Bt[n][k], At[m][k], acc[ai][bj][m][n], 0, 0, 0); __builtin_amdgcn_s_setprio(0); } while (0)
; #define PG8_WAIT_V(n) asm volatile("s_waitcnt vmcnt(" #n ")" ::: "memory")
; #define PG8_WAIT_L(n) asm volatile("s_waitcnt lgkmcnt(" #n ")" ::: "memory")
; #define PG8_BAR __builtin_amdgcn_s_barrier()
; #define PG8_SCHED __builtin_amdgcn_sched_barrier(0)
; template <class Epi>
; __device__ __forceinline__ void gemm_phase(PG8_LAS unsigned char* lds, const Gemm g, const StaticOrder& S, const Epi& E, const int wave_s) {
;     ...
;             const bool last = (t == nt - 2);
;             const char* a1 = cA + (size_t)(t + 1) * kstep;
;             const char* a2 = last ? nA : cA + (size_t)(t + 2) * kstep; const char* b2 = last ? nB : cB + (size_t)(t + 2) * kstep;
;             const char* a3 = a2 + kstep; const char* b3 = b2 + kstep;
;             PG8_LDB(B0, 0, 0); PG8_LDB(B1, 0, 1); PG8_SCHED; PG8_LDA(At, 0, 0); PG8_STAGE(PG8_SA(1, 1), a1 + hstepA, voffA);
;             PG8_WAIT_V(8); PG8_WAIT_L(0); PG8_BAR; PG8_MMA(0, 0, At, B0); PG8_MMA(0, 1, At, B1); PG8_BAR; PG8_SCHED;
;             PG8_LDA(At, 0, 1); PG8_STAGE(PG8_SB(0, 0), b2, voffB); PG8_STAGE(PG8_SB(0, 1), b2 + hstepB, voffB); PG8_STAGE(PG8_SA(0, 0), a2, voffA);
;             PG8_WAIT_V(8); PG8_WAIT_L(0); PG8_BAR; PG8_MMA(1, 0, At, B0); PG8_MMA(1, 1, At, B1); PG8_BAR; PG8_SCHED;
.Lg3_prio_done:
.LBB0_651:
	s_add_i32 s72, 0, 0x10000
	v_add_u32_e32 v97, s72, v159
	ds_read_b128 v[150:153], v97
	ds_read_b128 v[154:157], v97 offset:1024
	ds_read_b128 v[162:165], v97 offset:2048
	ds_read_b128 v[166:169], v97 offset:3072
	s_add_i32 s48, s6, 2
	s_add_u32 s49, s44, 0x80
	s_addc_u32 s7, s45, 0
	s_cmp_eq_u32 s37, s6
	s_cselect_b32 s7, s87, s7
	s_cselect_b32 s6, s86, s49
	s_cselect_b32 s51, s89, s47
	s_cselect_b32 s50, s88, s46
	s_add_i32 s49, 0, 0x14000
	v_add_u32_e32 v97, s49, v159
	ds_read_b128 v[170:173], v97
	ds_read_b128 v[174:177], v97 offset:1024
	ds_read_b128 v[178:181], v97 offset:2048
	ds_read_b128 v[182:185], v97 offset:3072
	v_lshl_add_u64 v[226:227], s[44:45], 0, v[140:141]
	s_add_i32 m0, s8, 0xc000
	ds_read_b128 v[186:189], v160
	ds_read_b128 v[190:193], v160 offset:1024
	ds_read_b128 v[194:197], v160 offset:2048
	ds_read_b128 v[198:201], v160 offset:3072
	ds_read_b128 v[202:205], v160 offset:4096
	ds_read_b128 v[206:209], v160 offset:5120
	ds_read_b128 v[218:221], v160 offset:6144
	ds_read_b128 v[222:225], v160 offset:7168
	global_load_lds_dwordx4 v[226:227], off
	v_lshl_add_u64 v[226:227], s[44:45], 0, v[142:143]
	s_add_i32 m0, s8, 0xe000
	s_nop 0
	global_load_lds_dwordx4 v[226:227], off
	s_waitcnt vmcnt(8)
	s_waitcnt lgkmcnt(0)
	s_barrier
	s_waitcnt lgkmcnt(0)
	v_mfma_f32_16x16x32_bf16 v[130:133], v[150:153], v[186:189], v[130:133]
	v_mfma_f32_16x16x32_bf16 v[126:129], v[162:165], v[186:189], v[126:129]
	v_mfma_f32_16x16x32_bf16 v[114:117], v[150:153], v[194:197], v[114:117]
	v_mfma_f32_16x16x32_bf16 v[110:113], v[162:165], v[194:197], v[110:113]
	v_mfma_f32_16x16x32_bf16 v[98:101], v[150:153], v[202:205], v[98:101]
	v_mfma_f32_16x16x32_bf16 v[92:95], v[162:165], v[202:205], v[92:95]
	v_mfma_f32_16x16x32_bf16 v[80:83], v[150:153], v[218:221], v[80:83]
	v_mfma_f32_16x16x32_bf16 v[76:79], v[162:165], v[218:221], v[76:79]
	v_mfma_f32_16x16x32_bf16 v[130:133], v[154:157], v[190:193], v[130:133]
	v_mfma_f32_16x16x32_bf16 v[126:129], v[166:169], v[190:193], v[126:129]
	v_mfma_f32_16x16x32_bf16 v[114:117], v[154:157], v[198:201], v[114:117]
	v_mfma_f32_16x16x32_bf16 v[110:113], v[166:169], v[198:201], v[110:113]
	v_mfma_f32_16x16x32_bf16 v[98:101], v[154:157], v[206:209], v[98:101]
	v_mfma_f32_16x16x32_bf16 v[92:95], v[166:169], v[206:209], v[92:95]
	v_mfma_f32_16x16x32_bf16 v[80:83], v[154:157], v[222:225], v[80:83]
	v_mfma_f32_16x16x32_bf16 v[76:79], v[166:169], v[222:225], v[76:79]
	v_mfma_f32_16x16x32_bf16 v[122:125], v[170:173], v[186:189], v[122:125]
	v_mfma_f32_16x16x32_bf16 v[118:121], v[178:181], v[186:189], v[118:121]
	v_mfma_f32_16x16x32_bf16 v[106:109], v[170:173], v[194:197], v[106:109]
	v_mfma_f32_16x16x32_bf16 v[102:105], v[178:181], v[194:197], v[102:105]
	v_mfma_f32_16x16x32_bf16 v[88:91], v[170:173], v[202:205], v[88:91]
	v_mfma_f32_16x16x32_bf16 v[84:87], v[178:181], v[202:205], v[84:87]
	v_mfma_f32_16x16x32_bf16 v[72:75], v[170:173], v[218:221], v[72:75]
	v_mfma_f32_16x16x32_bf16 v[68:71], v[178:181], v[218:221], v[68:71]
	v_mfma_f32_16x16x32_bf16 v[122:125], v[174:177], v[190:193], v[122:125]
	v_mfma_f32_16x16x32_bf16 v[118:121], v[182:185], v[190:193], v[118:121]
	v_mfma_f32_16x16x32_bf16 v[106:109], v[174:177], v[198:201], v[106:109]
	v_mfma_f32_16x16x32_bf16 v[102:105], v[182:185], v[198:201], v[102:105]
	v_mfma_f32_16x16x32_bf16 v[88:91], v[174:177], v[206:209], v[88:91]
	v_mfma_f32_16x16x32_bf16 v[84:87], v[182:185], v[206:209], v[84:87]
	v_mfma_f32_16x16x32_bf16 v[72:75], v[174:177], v[222:225], v[72:75]
	v_mfma_f32_16x16x32_bf16 v[68:71], v[182:185], v[222:225], v[68:71]
	s_barrier
	s_add_i32 s72, s72, s5
	v_lshl_add_u64 v[226:227], s[50:51], 0, v[210:211]
	s_mov_b32 m0, s72
	ds_read_b128 v[186:189], v160 offset:16384
	ds_read_b128 v[190:193], v160 offset:17408
	ds_read_b128 v[194:197], v160 offset:18432
	ds_read_b128 v[198:201], v160 offset:19456
	ds_read_b128 v[202:205], v160 offset:20480
	ds_read_b128 v[206:209], v160 offset:21504
	ds_read_b128 v[218:221], v160 offset:22528
	ds_read_b128 v[222:225], v160 offset:23552
	global_load_lds_dwordx4 v[226:227], off
	s_add_i32 m0, s72, 0x2000
	v_lshl_add_u64 v[228:229], s[50:51], 0, v[138:139]
	s_add_u32 s50, s50, s60
	s_addc_u32 s51, s51, s61
	s_add_i32 s49, s49, s5
	global_load_lds_dwordx4 v[228:229], off
	v_lshl_add_u64 v[230:231], s[50:51], 0, v[210:211]
	s_mov_b32 m0, s49
	v_lshl_add_u64 v[232:233], s[50:51], 0, v[138:139]
	global_load_lds_dwordx4 v[230:231], off
	s_add_i32 m0, s49, 0x2000
	v_lshl_add_u64 v[242:243], s[6:7], 0, v[134:135]
	global_load_lds_dwordx4 v[232:233], off
	s_mov_b32 m0, s8
	v_lshl_add_u64 v[244:245], s[6:7], 0, v[136:137]
	global_load_lds_dwordx4 v[242:243], off
	s_mov_b32 m0, s9
	s_nop 0
	global_load_lds_dwordx4 v[244:245], off
	s_waitcnt vmcnt(8)
	s_waitcnt lgkmcnt(0)
	s_barrier
; #define PG8_STAGE(bufoff, gbase, voff) do { _Pragma("unroll") for (int _i = 0; _i < 2; ++_i) \
;         __builtin_amdgcn_global_load_lds((const unsigned*)((const char*)(gbase) + (voff)[_i]), (PG8_LAS unsigned*)(lds + (bufoff) + ldsw + _i * 8192), 16, 0, 0); } while (0)
; #define PG8_LDA(dst, b, h) do { _Pragma("unroll") for (int m = 0; m < 4; ++m) _Pragma("unroll") for (int k = 0; k < 2; ++k) dst[m][k] = *(const PG8_LAS bf16x8*)(lds + PG8_SA(b, h) + aoff + m * 2048 + k * 1024); } while (0)
; #define PG8_LDB(dst, b, h) do { _Pragma("unroll") for (int n = 0; n < 2; ++n) _Pragma("unroll") for (int k = 0; k < 2; ++k) dst[n][k] = *(const PG8_LAS bf16x8*)(lds + PG8_SB(b, h) + boff + n * 2048 + k * 1024); } while (0)
; #define PG8_MMA(ai, bj, At, Bt) do { __builtin_amdgcn_s_setprio(1); _Pragma("unroll") for (int m = 0; m < 4; ++m) _Pragma("unroll") for (int n = 0; n < 2; ++n) _Pragma("unroll") for (int k = 0; k < 2; ++k) \
;         acc[ai][bj][m][n] = __builtin_amdgcn_mfma_f32_16x16x32_bf16(Bt[n][k], At[m][k], acc[ai][bj][m][n], 0, 0, 0); __builtin_amdgcn_s_setprio(0); } while (0)
; #define PG8_WAIT_V(n) asm volatile("s_waitcnt vmcnt(" #n ")" ::: "memory")
; #define PG8_WAIT_L(n) asm volatile("s_waitcnt lgkmcnt(" #n ")" ::: "memory")
; #define PG8_BAR __builtin_amdgcn_s_barrier()
; #define PG8_SCHED __builtin_amdgcn_sched_barrier(0)
; template <class Epi>
; __device__ __forceinline__ void gemm_phase(PG8_LAS unsigned char* lds, const Gemm g, const StaticOrder& S, const Epi& E, const int wave_s) {
;     ...
;             PG8_WAIT_V(8); PG8_WAIT_L(0); PG8_BAR; PG8_MMA(1, 0, At, B0); PG8_MMA(1, 1, At, B1); PG8_BAR; PG8_SCHED;
;             PG8_LDB(B0, 1, 0); PG8_LDB(B1, 1, 1); PG8_SCHED; PG8_LDA(At, 1, 0); PG8_STAGE(PG8_SA(0, 1), a2 + hstepA, voffA);
;             PG8_WAIT_V(8); PG8_WAIT_L(0); PG8_BAR; PG8_MMA(0, 0, At, B0); PG8_MMA(0, 1, At, B1); PG8_BAR; PG8_SCHED;
	s_waitcnt lgkmcnt(0)
	v_mfma_f32_16x16x32_bf16 v[64:67], v[150:153], v[186:189], v[64:67]
	v_mfma_f32_16x16x32_bf16 v[60:63], v[162:165], v[186:189], v[60:63]
	v_mfma_f32_16x16x32_bf16 v[48:51], v[150:153], v[194:197], v[48:51]
	v_mfma_f32_16x16x32_bf16 v[44:47], v[162:165], v[194:197], v[44:47]
	v_mfma_f32_16x16x32_bf16 v[32:35], v[150:153], v[202:205], v[32:35]
	v_mfma_f32_16x16x32_bf16 v[28:31], v[162:165], v[202:205], v[28:31]
	v_mfma_f32_16x16x32_bf16 v[16:19], v[150:153], v[218:221], v[16:19]
	v_mfma_f32_16x16x32_bf16 v[12:15], v[162:165], v[218:221], v[12:15]
	v_mfma_f32_16x16x32_bf16 v[64:67], v[154:157], v[190:193], v[64:67]
	v_mfma_f32_16x16x32_bf16 v[60:63], v[166:169], v[190:193], v[60:63]
	v_mfma_f32_16x16x32_bf16 v[48:51], v[154:157], v[198:201], v[48:51]
	v_mfma_f32_16x16x32_bf16 v[44:47], v[166:169], v[198:201], v[44:47]
	v_mfma_f32_16x16x32_bf16 v[32:35], v[154:157], v[206:209], v[32:35]
	v_mfma_f32_16x16x32_bf16 v[28:31], v[166:169], v[206:209], v[28:31]
	v_mfma_f32_16x16x32_bf16 v[16:19], v[154:157], v[222:225], v[16:19]
	v_mfma_f32_16x16x32_bf16 v[12:15], v[166:169], v[222:225], v[12:15]
	v_mfma_f32_16x16x32_bf16 v[56:59], v[170:173], v[186:189], v[56:59]
	v_mfma_f32_16x16x32_bf16 v[52:55], v[178:181], v[186:189], v[52:55]
	v_mfma_f32_16x16x32_bf16 v[40:43], v[170:173], v[194:197], v[40:43]
	v_mfma_f32_16x16x32_bf16 v[36:39], v[178:181], v[194:197], v[36:39]
	v_mfma_f32_16x16x32_bf16 v[24:27], v[170:173], v[202:205], v[24:27]
	v_mfma_f32_16x16x32_bf16 v[20:23], v[178:181], v[202:205], v[20:23]
	v_mfma_f32_16x16x32_bf16 v[8:11], v[170:173], v[218:221], v[8:11]
	v_mfma_f32_16x16x32_bf16 v[4:7], v[178:181], v[218:221], v[4:7]
	v_mfma_f32_16x16x32_bf16 v[56:59], v[174:177], v[190:193], v[56:59]
	v_mfma_f32_16x16x32_bf16 v[52:55], v[182:185], v[190:193], v[52:55]
	v_mfma_f32_16x16x32_bf16 v[40:43], v[174:177], v[198:201], v[40:43]
	v_mfma_f32_16x16x32_bf16 v[36:39], v[182:185], v[198:201], v[36:39]
	v_mfma_f32_16x16x32_bf16 v[24:27], v[174:177], v[206:209], v[24:27]
	v_mfma_f32_16x16x32_bf16 v[20:23], v[182:185], v[206:209], v[20:23]
	v_mfma_f32_16x16x32_bf16 v[8:11], v[174:177], v[222:225], v[8:11]
	v_mfma_f32_16x16x32_bf16 v[4:7], v[182:185], v[222:225], v[4:7]
	s_barrier
	s_add_i32 s49, 0, 0x18000
	v_add_u32_e32 v97, s49, v159
	s_add_i32 s50, 0, 0x1c000
	ds_read_b128 v[150:153], v97
	ds_read_b128 v[154:157], v97 offset:1024
	ds_read_b128 v[162:165], v97 offset:2048
	ds_read_b128 v[166:169], v97 offset:3072
	v_add_u32_e32 v97, s50, v159
	ds_read_b128 v[170:173], v97
	ds_read_b128 v[174:177], v97 offset:1024
	ds_read_b128 v[178:181], v97 offset:2048
	ds_read_b128 v[182:185], v97 offset:3072
	s_add_u32 s6, s6, s20
	s_addc_u32 s7, s7, s21
	s_mov_b32 m0, s10
	v_lshl_add_u64 v[246:247], s[6:7], 0, v[134:135]
	ds_read_b128 v[186:189], v160 offset:32768
	ds_read_b128 v[190:193], v160 offset:33792
	ds_read_b128 v[194:197], v160 offset:34816
	ds_read_b128 v[198:201], v160 offset:35840
	ds_read_b128 v[202:205], v160 offset:36864
	ds_read_b128 v[206:209], v160 offset:37888
	ds_read_b128 v[218:221], v160 offset:38912
	ds_read_b128 v[222:225], v160 offset:39936
	global_load_lds_dwordx4 v[246:247], off
	v_lshl_add_u64 v[246:247], s[6:7], 0, v[136:137]
	s_mov_b32 m0, s11
	s_nop 0
	global_load_lds_dwordx4 v[246:247], off
	s_waitcnt vmcnt(8)
	s_waitcnt lgkmcnt(0)
	s_barrier
	s_waitcnt lgkmcnt(0)
	v_mfma_f32_16x16x32_bf16 v[130:133], v[150:153], v[186:189], v[130:133]
	v_mfma_f32_16x16x32_bf16 v[126:129], v[162:165], v[186:189], v[126:129]
	v_mfma_f32_16x16x32_bf16 v[114:117], v[150:153], v[194:197], v[114:117]
	v_mfma_f32_16x16x32_bf16 v[110:113], v[162:165], v[194:197], v[110:113]
	v_mfma_f32_16x16x32_bf16 v[98:101], v[150:153], v[202:205], v[98:101]
	v_mfma_f32_16x16x32_bf16 v[92:95], v[162:165], v[202:205], v[92:95]
	v_mfma_f32_16x16x32_bf16 v[80:83], v[150:153], v[218:221], v[80:83]
	v_mfma_f32_16x16x32_bf16 v[76:79], v[162:165], v[218:221], v[76:79]
	v_mfma_f32_16x16x32_bf16 v[130:133], v[154:157], v[190:193], v[130:133]
	v_mfma_f32_16x16x32_bf16 v[126:129], v[166:169], v[190:193], v[126:129]
	v_mfma_f32_16x16x32_bf16 v[114:117], v[154:157], v[198:201], v[114:117]
	v_mfma_f32_16x16x32_bf16 v[110:113], v[166:169], v[198:201], v[110:113]
	v_mfma_f32_16x16x32_bf16 v[98:101], v[154:157], v[206:209], v[98:101]
	v_mfma_f32_16x16x32_bf16 v[92:95], v[166:169], v[206:209], v[92:95]
	v_mfma_f32_16x16x32_bf16 v[80:83], v[154:157], v[222:225], v[80:83]
	v_mfma_f32_16x16x32_bf16 v[76:79], v[166:169], v[222:225], v[76:79]
	v_mfma_f32_16x16x32_bf16 v[122:125], v[170:173], v[186:189], v[122:125]
	v_mfma_f32_16x16x32_bf16 v[118:121], v[178:181], v[186:189], v[118:121]
	v_mfma_f32_16x16x32_bf16 v[106:109], v[170:173], v[194:197], v[106:109]
	v_mfma_f32_16x16x32_bf16 v[102:105], v[178:181], v[194:197], v[102:105]
	v_mfma_f32_16x16x32_bf16 v[88:91], v[170:173], v[202:205], v[88:91]
	v_mfma_f32_16x16x32_bf16 v[84:87], v[178:181], v[202:205], v[84:87]
	v_mfma_f32_16x16x32_bf16 v[72:75], v[170:173], v[218:221], v[72:75]
	v_mfma_f32_16x16x32_bf16 v[68:71], v[178:181], v[218:221], v[68:71]
	v_mfma_f32_16x16x32_bf16 v[122:125], v[174:177], v[190:193], v[122:125]
	v_mfma_f32_16x16x32_bf16 v[118:121], v[182:185], v[190:193], v[118:121]
	v_mfma_f32_16x16x32_bf16 v[106:109], v[174:177], v[198:201], v[106:109]
	v_mfma_f32_16x16x32_bf16 v[102:105], v[182:185], v[198:201], v[102:105]
	v_mfma_f32_16x16x32_bf16 v[88:91], v[174:177], v[206:209], v[88:91]
	v_mfma_f32_16x16x32_bf16 v[84:87], v[182:185], v[206:209], v[84:87]
	v_mfma_f32_16x16x32_bf16 v[72:75], v[174:177], v[222:225], v[72:75]
	v_mfma_f32_16x16x32_bf16 v[68:71], v[182:185], v[222:225], v[68:71]
	s_barrier
; #define PG8_STAGE(bufoff, gbase, voff) do { _Pragma("unroll") for (int _i = 0; _i < 2; ++_i) \
;         __builtin_amdgcn_global_load_lds((const unsigned*)((const char*)(gbase) + (voff)[_i]), (PG8_LAS unsigned*)(lds + (bufoff) + ldsw + _i * 8192), 16, 0, 0); } while (0)
; #define PG8_LDA(dst, b, h) do { _Pragma("unroll") for (int m = 0; m < 4; ++m) _Pragma("unroll") for (int k = 0; k < 2; ++k) dst[m][k] = *(const PG8_LAS bf16x8*)(lds + PG8_SA(b, h) + aoff + m * 2048 + k * 1024); } while (0)
; #define PG8_MMA(ai, bj, At, Bt) do { __builtin_amdgcn_s_setprio(1); _Pragma("unroll") for (int m = 0; m < 4; ++m) _Pragma("unroll") for (int n = 0; n < 2; ++n) _Pragma("unroll") for (int k = 0; k < 2; ++k) \
;         acc[ai][bj][m][n] = __builtin_amdgcn_mfma_f32_16x16x32_bf16(Bt[n][k], At[m][k], acc[ai][bj][m][n], 0, 0, 0); __builtin_amdgcn_s_setprio(0); } while (0)
; #define PG8_WAIT_V(n) asm volatile("s_waitcnt vmcnt(" #n ")" ::: "memory")
; #define PG8_WAIT_L(n) asm volatile("s_waitcnt lgkmcnt(" #n ")" ::: "memory")
; #define PG8_BAR __builtin_amdgcn_s_barrier()
; #define PG8_SCHED __builtin_amdgcn_sched_barrier(0)
; template <class Epi>
; __device__ __forceinline__ void gemm_phase(PG8_LAS unsigned char* lds, const Gemm g, const StaticOrder& S, const Epi& E, const int wave_s) {
;     ...
;             PG8_LDA(At, 1, 1); PG8_STAGE(PG8_SB(1, 0), b3, voffB); PG8_STAGE(PG8_SB(1, 1), b3 + hstepB, voffB); PG8_STAGE(PG8_SA(1, 0), a3, voffA);
;             PG8_WAIT_V(8); PG8_WAIT_L(0); PG8_BAR; PG8_MMA(1, 0, At, B0); PG8_MMA(1, 1, At, B1); PG8_BAR; PG8_SCHED;
;         }
	s_add_i32 s6, s49, s5
	v_lshl_add_u64 v[226:227], v[226:227], 0, s[52:53]
	s_mov_b32 m0, s6
	ds_read_b128 v[186:189], v160 offset:49152
	ds_read_b128 v[190:193], v160 offset:50176
	ds_read_b128 v[194:197], v160 offset:51200
	ds_read_b128 v[198:201], v160 offset:52224
	ds_read_b128 v[202:205], v160 offset:53248
	ds_read_b128 v[206:209], v160 offset:54272
	ds_read_b128 v[218:221], v160 offset:55296
	ds_read_b128 v[222:225], v160 offset:56320
	global_load_lds_dwordx4 v[226:227], off
	v_lshl_add_u64 v[226:227], v[228:229], 0, s[52:53]
	s_add_i32 m0, s6, 0x2000
	s_add_i32 s6, s50, s5
	global_load_lds_dwordx4 v[226:227], off
	v_lshl_add_u64 v[226:227], v[230:231], 0, s[52:53]
	s_mov_b32 m0, s6
	s_nop 0
	global_load_lds_dwordx4 v[226:227], off
	v_lshl_add_u64 v[226:227], v[232:233], 0, s[52:53]
	s_add_i32 m0, s6, 0x2000
	s_nop 0
	global_load_lds_dwordx4 v[226:227], off
	v_lshl_add_u64 v[226:227], v[242:243], 0, s[52:53]
	s_mov_b32 m0, s27
	s_nop 0
	global_load_lds_dwordx4 v[226:227], off
	v_lshl_add_u64 v[226:227], v[244:245], 0, s[52:53]
	s_mov_b32 m0, s36
	s_nop 0
	global_load_lds_dwordx4 v[226:227], off
	s_waitcnt vmcnt(8)
	s_waitcnt lgkmcnt(0)
	s_barrier
	s_waitcnt lgkmcnt(0)
	v_mfma_f32_16x16x32_bf16 v[64:67], v[150:153], v[186:189], v[64:67]
	v_mfma_f32_16x16x32_bf16 v[60:63], v[162:165], v[186:189], v[60:63]
	s_add_u32 s44, s44, 0x100
	s_addc_u32 s45, s45, 0
	s_add_u32 s46, s46, 0x100
	s_addc_u32 s47, s47, 0
	s_mov_b32 s6, s48
	s_cmp_ge_i32 s48, s25
	v_mfma_f32_16x16x32_bf16 v[48:51], v[150:153], v[194:197], v[48:51]
	v_mfma_f32_16x16x32_bf16 v[44:47], v[162:165], v[194:197], v[44:47]
	v_mfma_f32_16x16x32_bf16 v[32:35], v[150:153], v[202:205], v[32:35]
	v_mfma_f32_16x16x32_bf16 v[28:31], v[162:165], v[202:205], v[28:31]
	v_mfma_f32_16x16x32_bf16 v[16:19], v[150:153], v[218:221], v[16:19]
	v_mfma_f32_16x16x32_bf16 v[12:15], v[162:165], v[218:221], v[12:15]
	v_mfma_f32_16x16x32_bf16 v[64:67], v[154:157], v[190:193], v[64:67]
	v_mfma_f32_16x16x32_bf16 v[60:63], v[166:169], v[190:193], v[60:63]
	v_mfma_f32_16x16x32_bf16 v[48:51], v[154:157], v[198:201], v[48:51]
	v_mfma_f32_16x16x32_bf16 v[44:47], v[166:169], v[198:201], v[44:47]
	v_mfma_f32_16x16x32_bf16 v[32:35], v[154:157], v[206:209], v[32:35]
	v_mfma_f32_16x16x32_bf16 v[28:31], v[166:169], v[206:209], v[28:31]
	v_mfma_f32_16x16x32_bf16 v[16:19], v[154:157], v[222:225], v[16:19]
	v_mfma_f32_16x16x32_bf16 v[12:15], v[166:169], v[222:225], v[12:15]
	v_mfma_f32_16x16x32_bf16 v[56:59], v[170:173], v[186:189], v[56:59]
	v_mfma_f32_16x16x32_bf16 v[52:55], v[178:181], v[186:189], v[52:55]
	v_mfma_f32_16x16x32_bf16 v[40:43], v[170:173], v[194:197], v[40:43]
	v_mfma_f32_16x16x32_bf16 v[36:39], v[178:181], v[194:197], v[36:39]
	v_mfma_f32_16x16x32_bf16 v[24:27], v[170:173], v[202:205], v[24:27]
	v_mfma_f32_16x16x32_bf16 v[20:23], v[178:181], v[202:205], v[20:23]
	v_mfma_f32_16x16x32_bf16 v[8:11], v[170:173], v[218:221], v[8:11]
	v_mfma_f32_16x16x32_bf16 v[4:7], v[178:181], v[218:221], v[4:7]
	v_mfma_f32_16x16x32_bf16 v[56:59], v[174:177], v[190:193], v[56:59]
	v_mfma_f32_16x16x32_bf16 v[52:55], v[182:185], v[190:193], v[52:55]
	v_mfma_f32_16x16x32_bf16 v[40:43], v[174:177], v[198:201], v[40:43]
	v_mfma_f32_16x16x32_bf16 v[36:39], v[182:185], v[198:201], v[36:39]
	v_mfma_f32_16x16x32_bf16 v[24:27], v[174:177], v[206:209], v[24:27]
	v_mfma_f32_16x16x32_bf16 v[20:23], v[182:185], v[206:209], v[20:23]
	v_mfma_f32_16x16x32_bf16 v[8:11], v[174:177], v[222:225], v[8:11]
	v_mfma_f32_16x16x32_bf16 v[4:7], v[182:185], v[222:225], v[4:7]
	s_barrier
	s_cbranch_scc0 .LBB0_651
	s_setprio 0

; #define PG8_STAGE(bufoff, gbase, voff) do { _Pragma("unroll") for (int _i = 0; _i < 2; ++_i) \
;         __builtin_amdgcn_global_load_lds((const unsigned*)((const char*)(gbase) + (voff)[_i]), (PG8_LAS unsigned*)(lds + (bufoff) + ldsw + _i * 8192), 16, 0, 0); } while (0)
; #define PG8_LDA(dst, b, h) do { _Pragma("unroll") for (int m = 0; m < 4; ++m) _Pragma("unroll") for (int k = 0; k < 2; ++k) dst[m][k] = *(const PG8_LAS bf16x8*)(lds + PG8_SA(b, h) + aoff + m * 2048 + k * 1024); } while (0)
; #define PG8_LDB(dst, b, h) do { _Pragma("unroll") for (int n = 0; n < 2; ++n) _Pragma("unroll") for (int k = 0; k < 2; ++k) dst[n][k] = *(const PG8_LAS bf16x8*)(lds + PG8_SB(b, h) + boff + n * 2048 + k * 1024); } while (0)
; #define PG8_MMA(ai, bj, At, Bt) do { __builtin_amdgcn_s_setprio(1); _Pragma("unroll") for (int m = 0; m < 4; ++m) _Pragma("unroll") for (int n = 0; n < 2; ++n) _Pragma("unroll") for (int k = 0; k < 2; ++k) \
;         acc[ai][bj][m][n] = __builtin_amdgcn_mfma_f32_16x16x32_bf16(Bt[n][k], At[m][k], acc[ai][bj][m][n], 0, 0, 0); __builtin_amdgcn_s_setprio(0); } while (0)
; #define PG8_WAIT_V(n) asm volatile("s_waitcnt vmcnt(" #n ")" ::: "memory")
; #define PG8_WAIT_L(n) asm volatile("s_waitcnt lgkmcnt(" #n ")" ::: "memory")
; #define PG8_BAR __builtin_amdgcn_s_barrier()
; #define PG8_SCHED __builtin_amdgcn_sched_barrier(0)
; template <class Epi>
; __device__ __forceinline__ void gemm_phase(PG8_LAS unsigned char* lds, const Gemm g, const StaticOrder& S, const Epi& E, const int wave_s) {
;     ...
;             const bool last = (t == nt - 2);
;             const char* a1 = cA + (size_t)(t + 1) * kstep;
;             const char* a2 = last ? nA : cA + (size_t)(t + 2) * kstep; const char* b2 = last ? nB : cB + (size_t)(t + 2) * kstep;
;             const char* a3 = a2 + kstep; const char* b3 = b2 + kstep;
;             PG8_LDB(B0, 0, 0); PG8_LDB(B1, 0, 1); PG8_SCHED; PG8_LDA(At, 0, 0); PG8_STAGE(PG8_SA(1, 1), a1 + hstepA, voffA);
;             PG8_WAIT_V(8); PG8_WAIT_L(0); PG8_BAR; PG8_MMA(0, 0, At, B0); PG8_MMA(0, 1, At, B1); PG8_BAR; PG8_SCHED;
;             PG8_LDA(At, 0, 1); PG8_STAGE(PG8_SB(0, 0), b2, voffB); PG8_STAGE(PG8_SB(0, 1), b2 + hstepB, voffB); PG8_STAGE(PG8_SA(0, 0), a2, voffA);
;             PG8_WAIT_V(8); PG8_WAIT_L(0); PG8_BAR; PG8_MMA(1, 0, At, B0); PG8_MMA(1, 1, At, B1); PG8_BAR; PG8_SCHED;
.Lg4_prio_done:
.LBB0_765:
	s_add_i32 s57, 0, 0x10000
	v_add_u32_e32 v110, s57, v97
	ds_read_b128 v[98:101], v110
	ds_read_b128 v[102:105], v110 offset:1024
	ds_read_b128 v[106:109], v110 offset:2048
	ds_read_b128 v[110:113], v110 offset:3072
	s_add_i32 s46, s6, 2
	s_add_u32 s47, s44, 0x80
	s_addc_u32 s7, s45, 0
	s_cmp_eq_u32 s92, s6
	s_cselect_b32 s7, s85, s7
	s_cselect_b32 s6, s84, s47
	s_cselect_b32 s49, s87, s13
	s_cselect_b32 s48, s86, s12
	s_add_i32 s47, 0, 0x14000
	v_add_u32_e32 v142, s47, v97
	ds_read_b128 v[118:121], v142
	ds_read_b128 v[122:125], v142 offset:1024
	ds_read_b128 v[138:141], v142 offset:2048
	ds_read_b128 v[142:145], v142 offset:3072
	v_lshl_add_u64 v[194:195], s[44:45], 0, v[224:225]
	s_add_i32 m0, s27, 0xc000
	ds_read_b128 v[162:165], v242
	ds_read_b128 v[166:169], v242 offset:1024
	ds_read_b128 v[170:173], v242 offset:2048
	ds_read_b128 v[174:177], v242 offset:3072
	ds_read_b128 v[178:181], v242 offset:4096
	ds_read_b128 v[182:185], v242 offset:5120
	ds_read_b128 v[186:189], v242 offset:6144
	ds_read_b128 v[190:193], v242 offset:7168
	global_load_lds_dwordx4 v[194:195], off
	v_lshl_add_u64 v[194:195], s[44:45], 0, v[226:227]
	s_add_i32 m0, s27, 0xe000
	s_nop 0
	global_load_lds_dwordx4 v[194:195], off
	s_waitcnt vmcnt(8)
	s_waitcnt lgkmcnt(0)
	s_barrier
	s_waitcnt lgkmcnt(0)
	v_mfma_f32_16x16x32_bf16 v[158:161], v[98:101], v[162:165], v[158:161]
	v_mfma_f32_16x16x32_bf16 v[154:157], v[106:109], v[162:165], v[154:157]
	v_mfma_f32_16x16x32_bf16 v[134:137], v[98:101], v[170:173], v[134:137]
	v_mfma_f32_16x16x32_bf16 v[130:133], v[106:109], v[170:173], v[130:133]
	v_mfma_f32_16x16x32_bf16 v[92:95], v[98:101], v[178:181], v[92:95]
	v_mfma_f32_16x16x32_bf16 v[88:91], v[106:109], v[178:181], v[88:91]
	v_mfma_f32_16x16x32_bf16 v[76:79], v[98:101], v[186:189], v[76:79]
	v_mfma_f32_16x16x32_bf16 v[72:75], v[106:109], v[186:189], v[72:75]
	v_mfma_f32_16x16x32_bf16 v[158:161], v[102:105], v[166:169], v[158:161]
	v_mfma_f32_16x16x32_bf16 v[154:157], v[110:113], v[166:169], v[154:157]
	v_mfma_f32_16x16x32_bf16 v[134:137], v[102:105], v[174:177], v[134:137]
	v_mfma_f32_16x16x32_bf16 v[130:133], v[110:113], v[174:177], v[130:133]
	v_mfma_f32_16x16x32_bf16 v[92:95], v[102:105], v[182:185], v[92:95]
	v_mfma_f32_16x16x32_bf16 v[88:91], v[110:113], v[182:185], v[88:91]
	v_mfma_f32_16x16x32_bf16 v[76:79], v[102:105], v[190:193], v[76:79]
	v_mfma_f32_16x16x32_bf16 v[72:75], v[110:113], v[190:193], v[72:75]
	v_mfma_f32_16x16x32_bf16 v[150:153], v[118:121], v[162:165], v[150:153]
	v_mfma_f32_16x16x32_bf16 v[146:149], v[138:141], v[162:165], v[146:149]
	v_mfma_f32_16x16x32_bf16 v[126:129], v[118:121], v[170:173], v[126:129]
	v_mfma_f32_16x16x32_bf16 v[114:117], v[138:141], v[170:173], v[114:117]
	v_mfma_f32_16x16x32_bf16 v[84:87], v[118:121], v[178:181], v[84:87]
	v_mfma_f32_16x16x32_bf16 v[80:83], v[138:141], v[178:181], v[80:83]
	v_mfma_f32_16x16x32_bf16 v[68:71], v[118:121], v[186:189], v[68:71]
	v_mfma_f32_16x16x32_bf16 v[64:67], v[138:141], v[186:189], v[64:67]
	v_mfma_f32_16x16x32_bf16 v[150:153], v[122:125], v[166:169], v[150:153]
	v_mfma_f32_16x16x32_bf16 v[146:149], v[142:145], v[166:169], v[146:149]
	v_mfma_f32_16x16x32_bf16 v[126:129], v[122:125], v[174:177], v[126:129]
	v_mfma_f32_16x16x32_bf16 v[114:117], v[142:145], v[174:177], v[114:117]
	v_mfma_f32_16x16x32_bf16 v[84:87], v[122:125], v[182:185], v[84:87]
	v_mfma_f32_16x16x32_bf16 v[80:83], v[142:145], v[182:185], v[80:83]
	v_mfma_f32_16x16x32_bf16 v[68:71], v[122:125], v[190:193], v[68:71]
	v_mfma_f32_16x16x32_bf16 v[64:67], v[142:145], v[190:193], v[64:67]
	s_barrier
	s_add_i32 s57, s57, s16
	v_lshl_add_u64 v[194:195], s[48:49], 0, v[210:211]
	s_mov_b32 m0, s57
	ds_read_b128 v[162:165], v242 offset:16384
	ds_read_b128 v[166:169], v242 offset:17408
	ds_read_b128 v[170:173], v242 offset:18432
	ds_read_b128 v[174:177], v242 offset:19456
	ds_read_b128 v[178:181], v242 offset:20480
	ds_read_b128 v[182:185], v242 offset:21504
	ds_read_b128 v[186:189], v242 offset:22528
	ds_read_b128 v[190:193], v242 offset:23552
	global_load_lds_dwordx4 v[194:195], off
	s_add_i32 m0, s57, 0x2000
	v_lshl_add_u64 v[196:197], s[48:49], 0, v[222:223]
	s_add_u32 s48, s48, s20
	s_addc_u32 s49, s49, s21
	s_add_i32 s47, s47, s16
	global_load_lds_dwordx4 v[196:197], off
	v_lshl_add_u64 v[198:199], s[48:49], 0, v[210:211]
	s_mov_b32 m0, s47
	v_lshl_add_u64 v[200:201], s[48:49], 0, v[222:223]
	global_load_lds_dwordx4 v[198:199], off
	s_add_i32 m0, s47, 0x2000
	v_lshl_add_u64 v[202:203], s[6:7], 0, v[218:219]
	global_load_lds_dwordx4 v[200:201], off
	s_mov_b32 m0, s27
	v_lshl_add_u64 v[204:205], s[6:7], 0, v[220:221]
	global_load_lds_dwordx4 v[202:203], off
	s_mov_b32 m0, s36
	s_nop 0
	global_load_lds_dwordx4 v[204:205], off
	s_waitcnt vmcnt(8)
	s_waitcnt lgkmcnt(0)
	s_barrier
; #define PG8_STAGE(bufoff, gbase, voff) do { _Pragma("unroll") for (int _i = 0; _i < 2; ++_i) \
;         __builtin_amdgcn_global_load_lds((const unsigned*)((const char*)(gbase) + (voff)[_i]), (PG8_LAS unsigned*)(lds + (bufoff) + ldsw + _i * 8192), 16, 0, 0); } while (0)
; #define PG8_LDA(dst, b, h) do { _Pragma("unroll") for (int m = 0; m < 4; ++m) _Pragma("unroll") for (int k = 0; k < 2; ++k) dst[m][k] = *(const PG8_LAS bf16x8*)(lds + PG8_SA(b, h) + aoff + m * 2048 + k * 1024); } while (0)
; #define PG8_LDB(dst, b, h) do { _Pragma("unroll") for (int n = 0; n < 2; ++n) _Pragma("unroll") for (int k = 0; k < 2; ++k) dst[n][k] = *(const PG8_LAS bf16x8*)(lds + PG8_SB(b, h) + boff + n * 2048 + k * 1024); } while (0)
; #define PG8_MMA(ai, bj, At, Bt) do { __builtin_amdgcn_s_setprio(1); _Pragma("unroll") for (int m = 0; m < 4; ++m) _Pragma("unroll") for (int n = 0; n < 2; ++n) _Pragma("unroll") for (int k = 0; k < 2; ++k) \
;         acc[ai][bj][m][n] = __builtin_amdgcn_mfma_f32_16x16x32_bf16(Bt[n][k], At[m][k], acc[ai][bj][m][n], 0, 0, 0); __builtin_amdgcn_s_setprio(0); } while (0)
; #define PG8_WAIT_V(n) asm volatile("s_waitcnt vmcnt(" #n ")" ::: "memory")
; #define PG8_WAIT_L(n) asm volatile("s_waitcnt lgkmcnt(" #n ")" ::: "memory")
; #define PG8_BAR __builtin_amdgcn_s_barrier()
; #define PG8_SCHED __builtin_amdgcn_sched_barrier(0)
; template <class Epi>
; __device__ __forceinline__ void gemm_phase(PG8_LAS unsigned char* lds, const Gemm g, const StaticOrder& S, const Epi& E, const int wave_s) {
;     ...
;             PG8_WAIT_V(8); PG8_WAIT_L(0); PG8_BAR; PG8_MMA(1, 0, At, B0); PG8_MMA(1, 1, At, B1); PG8_BAR; PG8_SCHED;
;             PG8_LDB(B0, 1, 0); PG8_LDB(B1, 1, 1); PG8_SCHED; PG8_LDA(At, 1, 0); PG8_STAGE(PG8_SA(0, 1), a2 + hstepA, voffA);
;             PG8_WAIT_V(8); PG8_WAIT_L(0); PG8_BAR; PG8_MMA(0, 0, At, B0); PG8_MMA(0, 1, At, B1); PG8_BAR; PG8_SCHED;
	s_waitcnt lgkmcnt(0)
	v_mfma_f32_16x16x32_bf16 v[60:63], v[98:101], v[162:165], v[60:63]
	v_mfma_f32_16x16x32_bf16 v[56:59], v[106:109], v[162:165], v[56:59]
	v_mfma_f32_16x16x32_bf16 v[44:47], v[98:101], v[170:173], v[44:47]
	v_mfma_f32_16x16x32_bf16 v[40:43], v[106:109], v[170:173], v[40:43]
	v_mfma_f32_16x16x32_bf16 v[28:31], v[98:101], v[178:181], v[28:31]
	v_mfma_f32_16x16x32_bf16 v[24:27], v[106:109], v[178:181], v[24:27]
	v_mfma_f32_16x16x32_bf16 v[12:15], v[98:101], v[186:189], v[12:15]
	v_mfma_f32_16x16x32_bf16 v[8:11], v[106:109], v[186:189], v[8:11]
	v_mfma_f32_16x16x32_bf16 v[60:63], v[102:105], v[166:169], v[60:63]
	v_mfma_f32_16x16x32_bf16 v[56:59], v[110:113], v[166:169], v[56:59]
	v_mfma_f32_16x16x32_bf16 v[44:47], v[102:105], v[174:177], v[44:47]
	v_mfma_f32_16x16x32_bf16 v[40:43], v[110:113], v[174:177], v[40:43]
	v_mfma_f32_16x16x32_bf16 v[28:31], v[102:105], v[182:185], v[28:31]
	v_mfma_f32_16x16x32_bf16 v[24:27], v[110:113], v[182:185], v[24:27]
	v_mfma_f32_16x16x32_bf16 v[12:15], v[102:105], v[190:193], v[12:15]
	v_mfma_f32_16x16x32_bf16 v[8:11], v[110:113], v[190:193], v[8:11]
	v_mfma_f32_16x16x32_bf16 v[52:55], v[118:121], v[162:165], v[52:55]
	v_mfma_f32_16x16x32_bf16 v[48:51], v[138:141], v[162:165], v[48:51]
	v_mfma_f32_16x16x32_bf16 v[36:39], v[118:121], v[170:173], v[36:39]
	v_mfma_f32_16x16x32_bf16 v[32:35], v[138:141], v[170:173], v[32:35]
	v_mfma_f32_16x16x32_bf16 v[20:23], v[118:121], v[178:181], v[20:23]
	v_mfma_f32_16x16x32_bf16 v[16:19], v[138:141], v[178:181], v[16:19]
	v_mfma_f32_16x16x32_bf16 v[4:7], v[118:121], v[186:189], v[4:7]
	v_mfma_f32_16x16x32_bf16 v[0:3], v[138:141], v[186:189], v[0:3]
	v_mfma_f32_16x16x32_bf16 v[52:55], v[122:125], v[166:169], v[52:55]
	v_mfma_f32_16x16x32_bf16 v[48:51], v[142:145], v[166:169], v[48:51]
	v_mfma_f32_16x16x32_bf16 v[36:39], v[122:125], v[174:177], v[36:39]
	v_mfma_f32_16x16x32_bf16 v[32:35], v[142:145], v[174:177], v[32:35]
	v_mfma_f32_16x16x32_bf16 v[20:23], v[122:125], v[182:185], v[20:23]
	v_mfma_f32_16x16x32_bf16 v[16:19], v[142:145], v[182:185], v[16:19]
	v_mfma_f32_16x16x32_bf16 v[4:7], v[122:125], v[190:193], v[4:7]
	v_mfma_f32_16x16x32_bf16 v[0:3], v[142:145], v[190:193], v[0:3]
	s_barrier
	s_add_i32 s47, 0, 0x18000
	s_add_i32 s48, 0, 0x1c000
	v_add_u32_e32 v110, s47, v97
	v_add_u32_e32 v142, s48, v97
	ds_read_b128 v[98:101], v110
	ds_read_b128 v[102:105], v110 offset:1024
	ds_read_b128 v[106:109], v110 offset:2048
	ds_read_b128 v[110:113], v110 offset:3072
	ds_read_b128 v[118:121], v142
	ds_read_b128 v[122:125], v142 offset:1024
	ds_read_b128 v[138:141], v142 offset:2048
	ds_read_b128 v[142:145], v142 offset:3072
	s_add_u32 s6, s6, s10
	s_addc_u32 s7, s7, s11
	s_mov_b32 m0, s37
	v_lshl_add_u64 v[206:207], s[6:7], 0, v[218:219]
	ds_read_b128 v[162:165], v242 offset:32768
	ds_read_b128 v[166:169], v242 offset:33792
	ds_read_b128 v[170:173], v242 offset:34816
	ds_read_b128 v[174:177], v242 offset:35840
	ds_read_b128 v[178:181], v242 offset:36864
	ds_read_b128 v[182:185], v242 offset:37888
	ds_read_b128 v[186:189], v242 offset:38912
	ds_read_b128 v[190:193], v242 offset:39936
	global_load_lds_dwordx4 v[206:207], off
	v_lshl_add_u64 v[206:207], s[6:7], 0, v[220:221]
	s_mov_b32 m0, s88
	s_nop 0
	global_load_lds_dwordx4 v[206:207], off
	s_waitcnt vmcnt(8)
	s_waitcnt lgkmcnt(0)
	s_barrier
	s_waitcnt lgkmcnt(0)
	v_mfma_f32_16x16x32_bf16 v[158:161], v[98:101], v[162:165], v[158:161]
	v_mfma_f32_16x16x32_bf16 v[154:157], v[106:109], v[162:165], v[154:157]
	v_mfma_f32_16x16x32_bf16 v[134:137], v[98:101], v[170:173], v[134:137]
	v_mfma_f32_16x16x32_bf16 v[130:133], v[106:109], v[170:173], v[130:133]
	v_mfma_f32_16x16x32_bf16 v[92:95], v[98:101], v[178:181], v[92:95]
	v_mfma_f32_16x16x32_bf16 v[88:91], v[106:109], v[178:181], v[88:91]
	v_mfma_f32_16x16x32_bf16 v[76:79], v[98:101], v[186:189], v[76:79]
	v_mfma_f32_16x16x32_bf16 v[72:75], v[106:109], v[186:189], v[72:75]
	v_mfma_f32_16x16x32_bf16 v[158:161], v[102:105], v[166:169], v[158:161]
	v_mfma_f32_16x16x32_bf16 v[154:157], v[110:113], v[166:169], v[154:157]
	v_mfma_f32_16x16x32_bf16 v[134:137], v[102:105], v[174:177], v[134:137]
	v_mfma_f32_16x16x32_bf16 v[130:133], v[110:113], v[174:177], v[130:133]
	v_mfma_f32_16x16x32_bf16 v[92:95], v[102:105], v[182:185], v[92:95]
	v_mfma_f32_16x16x32_bf16 v[88:91], v[110:113], v[182:185], v[88:91]
	v_mfma_f32_16x16x32_bf16 v[76:79], v[102:105], v[190:193], v[76:79]
	v_mfma_f32_16x16x32_bf16 v[72:75], v[110:113], v[190:193], v[72:75]
	v_mfma_f32_16x16x32_bf16 v[150:153], v[118:121], v[162:165], v[150:153]
	v_mfma_f32_16x16x32_bf16 v[146:149], v[138:141], v[162:165], v[146:149]
	v_mfma_f32_16x16x32_bf16 v[126:129], v[118:121], v[170:173], v[126:129]
	v_mfma_f32_16x16x32_bf16 v[114:117], v[138:141], v[170:173], v[114:117]
	v_mfma_f32_16x16x32_bf16 v[84:87], v[118:121], v[178:181], v[84:87]
	v_mfma_f32_16x16x32_bf16 v[80:83], v[138:141], v[178:181], v[80:83]
	v_mfma_f32_16x16x32_bf16 v[68:71], v[118:121], v[186:189], v[68:71]
	v_mfma_f32_16x16x32_bf16 v[64:67], v[138:141], v[186:189], v[64:67]
	v_mfma_f32_16x16x32_bf16 v[150:153], v[122:125], v[166:169], v[150:153]
	v_mfma_f32_16x16x32_bf16 v[146:149], v[142:145], v[166:169], v[146:149]
	v_mfma_f32_16x16x32_bf16 v[126:129], v[122:125], v[174:177], v[126:129]
	v_mfma_f32_16x16x32_bf16 v[114:117], v[142:145], v[174:177], v[114:117]
	v_mfma_f32_16x16x32_bf16 v[84:87], v[122:125], v[182:185], v[84:87]
	v_mfma_f32_16x16x32_bf16 v[80:83], v[142:145], v[182:185], v[80:83]
	v_mfma_f32_16x16x32_bf16 v[68:71], v[122:125], v[190:193], v[68:71]
	v_mfma_f32_16x16x32_bf16 v[64:67], v[142:145], v[190:193], v[64:67]
	s_barrier
; #define PG8_STAGE(bufoff, gbase, voff) do { _Pragma("unroll") for (int _i = 0; _i < 2; ++_i) \
;         __builtin_amdgcn_global_load_lds((const unsigned*)((const char*)(gbase) + (voff)[_i]), (PG8_LAS unsigned*)(lds + (bufoff) + ldsw + _i * 8192), 16, 0, 0); } while (0)
; #define PG8_LDA(dst, b, h) do { _Pragma("unroll") for (int m = 0; m < 4; ++m) _Pragma("unroll") for (int k = 0; k < 2; ++k) dst[m][k] = *(const PG8_LAS bf16x8*)(lds + PG8_SA(b, h) + aoff + m * 2048 + k * 1024); } while (0)
; #define PG8_MMA(ai, bj, At, Bt) do { __builtin_amdgcn_s_setprio(1); _Pragma("unroll") for (int m = 0; m < 4; ++m) _Pragma("unroll") for (int n = 0; n < 2; ++n) _Pragma("unroll") for (int k = 0; k < 2; ++k) \
;         acc[ai][bj][m][n] = __builtin_amdgcn_mfma_f32_16x16x32_bf16(Bt[n][k], At[m][k], acc[ai][bj][m][n], 0, 0, 0); __builtin_amdgcn_s_setprio(0); } while (0)
; #define PG8_WAIT_V(n) asm volatile("s_waitcnt vmcnt(" #n ")" ::: "memory")
; #define PG8_WAIT_L(n) asm volatile("s_waitcnt lgkmcnt(" #n ")" ::: "memory")
; #define PG8_BAR __builtin_amdgcn_s_barrier()
; #define PG8_SCHED __builtin_amdgcn_sched_barrier(0)
; template <class Epi>
; __device__ __forceinline__ void gemm_phase(PG8_LAS unsigned char* lds, const Gemm g, const StaticOrder& S, const Epi& E, const int wave_s) {
;     ...
;             PG8_LDA(At, 1, 1); PG8_STAGE(PG8_SB(1, 0), b3, voffB); PG8_STAGE(PG8_SB(1, 1), b3 + hstepB, voffB); PG8_STAGE(PG8_SA(1, 0), a3, voffA);
;             PG8_WAIT_V(8); PG8_WAIT_L(0); PG8_BAR; PG8_MMA(1, 0, At, B0); PG8_MMA(1, 1, At, B1); PG8_BAR; PG8_SCHED;
;         }
	s_add_i32 s6, s47, s16
	v_lshl_add_u64 v[194:195], v[194:195], 0, s[52:53]
	s_mov_b32 m0, s6
	ds_read_b128 v[162:165], v242 offset:49152
	ds_read_b128 v[166:169], v242 offset:50176
	ds_read_b128 v[170:173], v242 offset:51200
	ds_read_b128 v[174:177], v242 offset:52224
	ds_read_b128 v[178:181], v242 offset:53248
	ds_read_b128 v[182:185], v242 offset:54272
	ds_read_b128 v[186:189], v242 offset:55296
	ds_read_b128 v[190:193], v242 offset:56320
	global_load_lds_dwordx4 v[194:195], off
	v_lshl_add_u64 v[194:195], v[196:197], 0, s[52:53]
	s_add_i32 m0, s6, 0x2000
	s_add_i32 s6, s48, s16
	global_load_lds_dwordx4 v[194:195], off
	v_lshl_add_u64 v[194:195], v[198:199], 0, s[52:53]
	s_mov_b32 m0, s6
	s_nop 0
	global_load_lds_dwordx4 v[194:195], off
	v_lshl_add_u64 v[194:195], v[200:201], 0, s[52:53]
	s_add_i32 m0, s6, 0x2000
	s_nop 0
	global_load_lds_dwordx4 v[194:195], off
	v_lshl_add_u64 v[194:195], v[202:203], 0, s[52:53]
	s_mov_b32 m0, s93
	s_nop 0
	global_load_lds_dwordx4 v[194:195], off
	v_lshl_add_u64 v[194:195], v[204:205], 0, s[52:53]
	s_mov_b32 m0, s97
	s_nop 0
	global_load_lds_dwordx4 v[194:195], off
	s_waitcnt vmcnt(8)
	s_waitcnt lgkmcnt(0)
	s_barrier
	s_waitcnt lgkmcnt(0)
	v_mfma_f32_16x16x32_bf16 v[60:63], v[98:101], v[162:165], v[60:63]
	v_mfma_f32_16x16x32_bf16 v[56:59], v[106:109], v[162:165], v[56:59]
	s_add_u32 s44, s44, 0x100
	s_addc_u32 s45, s45, 0
	s_add_u32 s12, s12, 0x100
	s_addc_u32 s13, s13, 0
	s_mov_b32 s6, s46
	s_cmp_ge_i32 s46, s94
	v_mfma_f32_16x16x32_bf16 v[44:47], v[98:101], v[170:173], v[44:47]
	v_mfma_f32_16x16x32_bf16 v[40:43], v[106:109], v[170:173], v[40:43]
	v_mfma_f32_16x16x32_bf16 v[28:31], v[98:101], v[178:181], v[28:31]
	v_mfma_f32_16x16x32_bf16 v[24:27], v[106:109], v[178:181], v[24:27]
	v_mfma_f32_16x16x32_bf16 v[12:15], v[98:101], v[186:189], v[12:15]
	v_mfma_f32_16x16x32_bf16 v[8:11], v[106:109], v[186:189], v[8:11]
	v_mfma_f32_16x16x32_bf16 v[60:63], v[102:105], v[166:169], v[60:63]
	v_mfma_f32_16x16x32_bf16 v[56:59], v[110:113], v[166:169], v[56:59]
	v_mfma_f32_16x16x32_bf16 v[44:47], v[102:105], v[174:177], v[44:47]
	v_mfma_f32_16x16x32_bf16 v[40:43], v[110:113], v[174:177], v[40:43]
	v_mfma_f32_16x16x32_bf16 v[28:31], v[102:105], v[182:185], v[28:31]
	v_mfma_f32_16x16x32_bf16 v[24:27], v[110:113], v[182:185], v[24:27]
	v_mfma_f32_16x16x32_bf16 v[12:15], v[102:105], v[190:193], v[12:15]
	v_mfma_f32_16x16x32_bf16 v[8:11], v[110:113], v[190:193], v[8:11]
	v_mfma_f32_16x16x32_bf16 v[52:55], v[118:121], v[162:165], v[52:55]
	v_mfma_f32_16x16x32_bf16 v[48:51], v[138:141], v[162:165], v[48:51]
	v_mfma_f32_16x16x32_bf16 v[36:39], v[118:121], v[170:173], v[36:39]
	v_mfma_f32_16x16x32_bf16 v[32:35], v[138:141], v[170:173], v[32:35]
	v_mfma_f32_16x16x32_bf16 v[20:23], v[118:121], v[178:181], v[20:23]
	v_mfma_f32_16x16x32_bf16 v[16:19], v[138:141], v[178:181], v[16:19]
	v_mfma_f32_16x16x32_bf16 v[4:7], v[118:121], v[186:189], v[4:7]
	v_mfma_f32_16x16x32_bf16 v[0:3], v[138:141], v[186:189], v[0:3]
	v_mfma_f32_16x16x32_bf16 v[52:55], v[122:125], v[166:169], v[52:55]
	v_mfma_f32_16x16x32_bf16 v[48:51], v[142:145], v[166:169], v[48:51]
	v_mfma_f32_16x16x32_bf16 v[36:39], v[122:125], v[174:177], v[36:39]
	v_mfma_f32_16x16x32_bf16 v[32:35], v[142:145], v[174:177], v[32:35]
	v_mfma_f32_16x16x32_bf16 v[20:23], v[122:125], v[182:185], v[20:23]
	v_mfma_f32_16x16x32_bf16 v[16:19], v[142:145], v[182:185], v[16:19]
	v_mfma_f32_16x16x32_bf16 v[4:7], v[122:125], v[190:193], v[4:7]
	v_mfma_f32_16x16x32_bf16 v[0:3], v[142:145], v[190:193], v[0:3]
	s_barrier
	s_cbranch_scc0 .LBB0_765
	s_setprio 0

; #define PG8_STAGE(bufoff, gbase, voff) do { _Pragma("unroll") for (int _i = 0; _i < 2; ++_i) \
;         __builtin_amdgcn_global_load_lds((const unsigned*)((const char*)(gbase) + (voff)[_i]), (PG8_LAS unsigned*)(lds + (bufoff) + ldsw + _i * 8192), 16, 0, 0); } while (0)
; #define PG8_LDA(dst, b, h) do { _Pragma("unroll") for (int m = 0; m < 4; ++m) _Pragma("unroll") for (int k = 0; k < 2; ++k) dst[m][k] = *(const PG8_LAS bf16x8*)(lds + PG8_SA(b, h) + aoff + m * 2048 + k * 1024); } while (0)
; #define PG8_LDB(dst, b, h) do { _Pragma("unroll") for (int n = 0; n < 2; ++n) _Pragma("unroll") for (int k = 0; k < 2; ++k) dst[n][k] = *(const PG8_LAS bf16x8*)(lds + PG8_SB(b, h) + boff + n * 2048 + k * 1024); } while (0)
; #define PG8_MMA(ai, bj, At, Bt) do { __builtin_amdgcn_s_setprio(1); _Pragma("unroll") for (int m = 0; m < 4; ++m) _Pragma("unroll") for (int n = 0; n < 2; ++n) _Pragma("unroll") for (int k = 0; k < 2; ++k) \
;         acc[ai][bj][m][n] = __builtin_amdgcn_mfma_f32_16x16x32_bf16(Bt[n][k], At[m][k], acc[ai][bj][m][n], 0, 0, 0); __builtin_amdgcn_s_setprio(0); } while (0)
; #define PG8_WAIT_V(n) asm volatile("s_waitcnt vmcnt(" #n ")" ::: "memory")
; #define PG8_WAIT_L(n) asm volatile("s_waitcnt lgkmcnt(" #n ")" ::: "memory")
; #define PG8_BAR __builtin_amdgcn_s_barrier()
; #define PG8_SCHED __builtin_amdgcn_sched_barrier(0)
; template <class Epi>
; __device__ __forceinline__ void gemm_phase(PG8_LAS unsigned char* lds, const Gemm g, const StaticOrder& S, const Epi& E, const int wave_s) {
;     ...
;             const bool last = (t == nt - 2);
;             const char* a1 = cA + (size_t)(t + 1) * kstep;
;             const char* a2 = last ? nA : cA + (size_t)(t + 2) * kstep; const char* b2 = last ? nB : cB + (size_t)(t + 2) * kstep;
;             const char* a3 = a2 + kstep; const char* b3 = b2 + kstep;
;             PG8_LDB(B0, 0, 0); PG8_LDB(B1, 0, 1); PG8_SCHED; PG8_LDA(At, 0, 0); PG8_STAGE(PG8_SA(1, 1), a1 + hstepA, voffA);
;             PG8_WAIT_V(8); PG8_WAIT_L(0); PG8_BAR; PG8_MMA(0, 0, At, B0); PG8_MMA(0, 1, At, B1); PG8_BAR; PG8_SCHED;
;             PG8_LDA(At, 0, 1); PG8_STAGE(PG8_SB(0, 0), b2, voffB); PG8_STAGE(PG8_SB(0, 1), b2 + hstepB, voffB); PG8_STAGE(PG8_SA(0, 0), a2, voffA);
;             PG8_WAIT_V(8); PG8_WAIT_L(0); PG8_BAR; PG8_MMA(1, 0, At, B0); PG8_MMA(1, 1, At, B1); PG8_BAR; PG8_SCHED;
.Lgu_prio_done:
.LBB0_950:
	s_add_i32 s72, 0, 0x10000
	v_add_u32_e32 v145, s72, v141
	ds_read_b128 v[156:159], v145
	ds_read_b128 v[160:163], v145 offset:1024
	ds_read_b128 v[164:167], v145 offset:2048
	ds_read_b128 v[168:171], v145 offset:3072
	s_add_i32 s68, s6, 2
	s_add_u32 s69, s56, 0x80
	s_addc_u32 s7, s57, 0
	s_cmp_eq_u32 s60, s6
	s_cselect_b32 s7, s45, s7
	s_cselect_b32 s6, s44, s69
	s_cselect_b32 s71, s51, s67
	s_cselect_b32 s70, s50, s66
	s_add_i32 s69, 0, 0x14000
	v_add_u32_e32 v145, s69, v141
	ds_read_b128 v[172:175], v145
	ds_read_b128 v[176:179], v145 offset:1024
	ds_read_b128 v[180:183], v145 offset:2048
	ds_read_b128 v[184:187], v145 offset:3072
	v_lshl_add_u64 v[208:209], s[56:57], 0, v[136:137]
	s_add_i32 m0, s13, 0xc000
	ds_read_b128 v[188:191], v143
	ds_read_b128 v[192:195], v143 offset:1024
	ds_read_b128 v[196:199], v143 offset:2048
	ds_read_b128 v[200:203], v143 offset:3072
	ds_read_b128 v[204:207], v143 offset:4096
	ds_read_b128 v[218:221], v143 offset:5120
	ds_read_b128 v[222:225], v143 offset:6144
	ds_read_b128 v[226:229], v143 offset:7168
	global_load_lds_dwordx4 v[208:209], off
	v_lshl_add_u64 v[208:209], s[56:57], 0, v[138:139]
	s_add_i32 m0, s13, 0xe000
	s_nop 0
	global_load_lds_dwordx4 v[208:209], off
	s_waitcnt vmcnt(8)
	s_waitcnt lgkmcnt(0)
	s_barrier
	s_waitcnt lgkmcnt(0)
	v_mfma_f32_16x16x32_bf16 v[126:129], v[156:159], v[188:191], v[126:129]
	v_mfma_f32_16x16x32_bf16 v[122:125], v[164:167], v[188:191], v[122:125]
	v_mfma_f32_16x16x32_bf16 v[110:113], v[156:159], v[196:199], v[110:113]
	v_mfma_f32_16x16x32_bf16 v[106:109], v[164:167], v[196:199], v[106:109]
	v_mfma_f32_16x16x32_bf16 v[92:95], v[156:159], v[204:207], v[92:95]
	v_mfma_f32_16x16x32_bf16 v[88:91], v[164:167], v[204:207], v[88:91]
	v_mfma_f32_16x16x32_bf16 v[76:79], v[156:159], v[222:225], v[76:79]
	v_mfma_f32_16x16x32_bf16 v[72:75], v[164:167], v[222:225], v[72:75]
	v_mfma_f32_16x16x32_bf16 v[126:129], v[160:163], v[192:195], v[126:129]
	v_mfma_f32_16x16x32_bf16 v[122:125], v[168:171], v[192:195], v[122:125]
	v_mfma_f32_16x16x32_bf16 v[110:113], v[160:163], v[200:203], v[110:113]
	v_mfma_f32_16x16x32_bf16 v[106:109], v[168:171], v[200:203], v[106:109]
	v_mfma_f32_16x16x32_bf16 v[92:95], v[160:163], v[218:221], v[92:95]
	v_mfma_f32_16x16x32_bf16 v[88:91], v[168:171], v[218:221], v[88:91]
	v_mfma_f32_16x16x32_bf16 v[76:79], v[160:163], v[226:229], v[76:79]
	v_mfma_f32_16x16x32_bf16 v[72:75], v[168:171], v[226:229], v[72:75]
	v_mfma_f32_16x16x32_bf16 v[118:121], v[172:175], v[188:191], v[118:121]
	v_mfma_f32_16x16x32_bf16 v[114:117], v[180:183], v[188:191], v[114:117]
	v_mfma_f32_16x16x32_bf16 v[102:105], v[172:175], v[196:199], v[102:105]
	v_mfma_f32_16x16x32_bf16 v[98:101], v[180:183], v[196:199], v[98:101]
	v_mfma_f32_16x16x32_bf16 v[84:87], v[172:175], v[204:207], v[84:87]
	v_mfma_f32_16x16x32_bf16 v[80:83], v[180:183], v[204:207], v[80:83]
	v_mfma_f32_16x16x32_bf16 v[68:71], v[172:175], v[222:225], v[68:71]
	v_mfma_f32_16x16x32_bf16 v[64:67], v[180:183], v[222:225], v[64:67]
	v_mfma_f32_16x16x32_bf16 v[118:121], v[176:179], v[192:195], v[118:121]
	v_mfma_f32_16x16x32_bf16 v[114:117], v[184:187], v[192:195], v[114:117]
	v_mfma_f32_16x16x32_bf16 v[102:105], v[176:179], v[200:203], v[102:105]
	v_mfma_f32_16x16x32_bf16 v[98:101], v[184:187], v[200:203], v[98:101]
	v_mfma_f32_16x16x32_bf16 v[84:87], v[176:179], v[218:221], v[84:87]
	v_mfma_f32_16x16x32_bf16 v[80:83], v[184:187], v[218:221], v[80:83]
	v_mfma_f32_16x16x32_bf16 v[68:71], v[176:179], v[226:229], v[68:71]
	v_mfma_f32_16x16x32_bf16 v[64:67], v[184:187], v[226:229], v[64:67]
	s_barrier
	s_add_i32 s72, s72, s9
	v_lshl_add_u64 v[208:209], s[70:71], 0, v[210:211]
	s_mov_b32 m0, s72
	ds_read_b128 v[188:191], v143 offset:16384
	ds_read_b128 v[192:195], v143 offset:17408
	ds_read_b128 v[196:199], v143 offset:18432
	ds_read_b128 v[200:203], v143 offset:19456
	ds_read_b128 v[204:207], v143 offset:20480
	ds_read_b128 v[218:221], v143 offset:21504
	ds_read_b128 v[222:225], v143 offset:22528
	ds_read_b128 v[226:229], v143 offset:23552
	global_load_lds_dwordx4 v[208:209], off
	s_add_i32 m0, s72, 0x2000
	v_lshl_add_u64 v[230:231], s[70:71], 0, v[130:131]
	s_add_u32 s70, s70, s10
	s_addc_u32 s71, s71, s11
	s_add_i32 s69, s69, s9
	global_load_lds_dwordx4 v[230:231], off
	v_lshl_add_u64 v[232:233], s[70:71], 0, v[210:211]
	s_mov_b32 m0, s69
	v_lshl_add_u64 v[242:243], s[70:71], 0, v[130:131]
	global_load_lds_dwordx4 v[232:233], off
	s_add_i32 m0, s69, 0x2000
	v_lshl_add_u64 v[244:245], s[6:7], 0, v[134:135]
	global_load_lds_dwordx4 v[242:243], off
	s_mov_b32 m0, s13
	v_lshl_add_u64 v[246:247], s[6:7], 0, v[132:133]
	global_load_lds_dwordx4 v[244:245], off
	s_mov_b32 m0, s25
	s_nop 0
	global_load_lds_dwordx4 v[246:247], off
	s_waitcnt vmcnt(8)
	s_waitcnt lgkmcnt(0)
	s_barrier
; #define PG8_STAGE(bufoff, gbase, voff) do { _Pragma("unroll") for (int _i = 0; _i < 2; ++_i) \
;         __builtin_amdgcn_global_load_lds((const unsigned*)((const char*)(gbase) + (voff)[_i]), (PG8_LAS unsigned*)(lds + (bufoff) + ldsw + _i * 8192), 16, 0, 0); } while (0)
; #define PG8_LDA(dst, b, h) do { _Pragma("unroll") for (int m = 0; m < 4; ++m) _Pragma("unroll") for (int k = 0; k < 2; ++k) dst[m][k] = *(const PG8_LAS bf16x8*)(lds + PG8_SA(b, h) + aoff + m * 2048 + k * 1024); } while (0)
; #define PG8_LDB(dst, b, h) do { _Pragma("unroll") for (int n = 0; n < 2; ++n) _Pragma("unroll") for (int k = 0; k < 2; ++k) dst[n][k] = *(const PG8_LAS bf16x8*)(lds + PG8_SB(b, h) + boff + n * 2048 + k * 1024); } while (0)
; #define PG8_MMA(ai, bj, At, Bt) do { __builtin_amdgcn_s_setprio(1); _Pragma("unroll") for (int m = 0; m < 4; ++m) _Pragma("unroll") for (int n = 0; n < 2; ++n) _Pragma("unroll") for (int k = 0; k < 2; ++k) \
;         acc[ai][bj][m][n] = __builtin_amdgcn_mfma_f32_16x16x32_bf16(Bt[n][k], At[m][k], acc[ai][bj][m][n], 0, 0, 0); __builtin_amdgcn_s_setprio(0); } while (0)
; #define PG8_WAIT_V(n) asm volatile("s_waitcnt vmcnt(" #n ")" ::: "memory")
; #define PG8_WAIT_L(n) asm volatile("s_waitcnt lgkmcnt(" #n ")" ::: "memory")
; #define PG8_BAR __builtin_amdgcn_s_barrier()
; #define PG8_SCHED __builtin_amdgcn_sched_barrier(0)
; template <class Epi>
; __device__ __forceinline__ void gemm_phase(PG8_LAS unsigned char* lds, const Gemm g, const StaticOrder& S, const Epi& E, const int wave_s) {
;     ...
;             PG8_WAIT_V(8); PG8_WAIT_L(0); PG8_BAR; PG8_MMA(1, 0, At, B0); PG8_MMA(1, 1, At, B1); PG8_BAR; PG8_SCHED;
;             PG8_LDB(B0, 1, 0); PG8_LDB(B1, 1, 1); PG8_SCHED; PG8_LDA(At, 1, 0); PG8_STAGE(PG8_SA(0, 1), a2 + hstepA, voffA);
;             PG8_WAIT_V(8); PG8_WAIT_L(0); PG8_BAR; PG8_MMA(0, 0, At, B0); PG8_MMA(0, 1, At, B1); PG8_BAR; PG8_SCHED;
	s_waitcnt lgkmcnt(0)
	v_mfma_f32_16x16x32_bf16 v[60:63], v[156:159], v[188:191], v[60:63]
	v_mfma_f32_16x16x32_bf16 v[56:59], v[164:167], v[188:191], v[56:59]
	v_mfma_f32_16x16x32_bf16 v[44:47], v[156:159], v[196:199], v[44:47]
	v_mfma_f32_16x16x32_bf16 v[40:43], v[164:167], v[196:199], v[40:43]
	v_mfma_f32_16x16x32_bf16 v[28:31], v[156:159], v[204:207], v[28:31]
	v_mfma_f32_16x16x32_bf16 v[24:27], v[164:167], v[204:207], v[24:27]
	v_mfma_f32_16x16x32_bf16 v[12:15], v[156:159], v[222:225], v[12:15]
	v_mfma_f32_16x16x32_bf16 v[8:11], v[164:167], v[222:225], v[8:11]
	v_mfma_f32_16x16x32_bf16 v[60:63], v[160:163], v[192:195], v[60:63]
	v_mfma_f32_16x16x32_bf16 v[56:59], v[168:171], v[192:195], v[56:59]
	v_mfma_f32_16x16x32_bf16 v[44:47], v[160:163], v[200:203], v[44:47]
	v_mfma_f32_16x16x32_bf16 v[40:43], v[168:171], v[200:203], v[40:43]
	v_mfma_f32_16x16x32_bf16 v[28:31], v[160:163], v[218:221], v[28:31]
	v_mfma_f32_16x16x32_bf16 v[24:27], v[168:171], v[218:221], v[24:27]
	v_mfma_f32_16x16x32_bf16 v[12:15], v[160:163], v[226:229], v[12:15]
	v_mfma_f32_16x16x32_bf16 v[8:11], v[168:171], v[226:229], v[8:11]
	v_mfma_f32_16x16x32_bf16 v[52:55], v[172:175], v[188:191], v[52:55]
	v_mfma_f32_16x16x32_bf16 v[48:51], v[180:183], v[188:191], v[48:51]
	v_mfma_f32_16x16x32_bf16 v[36:39], v[172:175], v[196:199], v[36:39]
	v_mfma_f32_16x16x32_bf16 v[32:35], v[180:183], v[196:199], v[32:35]
	v_mfma_f32_16x16x32_bf16 v[20:23], v[172:175], v[204:207], v[20:23]
	v_mfma_f32_16x16x32_bf16 v[16:19], v[180:183], v[204:207], v[16:19]
	v_mfma_f32_16x16x32_bf16 v[4:7], v[172:175], v[222:225], v[4:7]
	v_mfma_f32_16x16x32_bf16 v[0:3], v[180:183], v[222:225], v[0:3]
	v_mfma_f32_16x16x32_bf16 v[52:55], v[176:179], v[192:195], v[52:55]
	v_mfma_f32_16x16x32_bf16 v[48:51], v[184:187], v[192:195], v[48:51]
	v_mfma_f32_16x16x32_bf16 v[36:39], v[176:179], v[200:203], v[36:39]
	v_mfma_f32_16x16x32_bf16 v[32:35], v[184:187], v[200:203], v[32:35]
	v_mfma_f32_16x16x32_bf16 v[20:23], v[176:179], v[218:221], v[20:23]
	v_mfma_f32_16x16x32_bf16 v[16:19], v[184:187], v[218:221], v[16:19]
	v_mfma_f32_16x16x32_bf16 v[4:7], v[176:179], v[226:229], v[4:7]
	v_mfma_f32_16x16x32_bf16 v[0:3], v[184:187], v[226:229], v[0:3]
	s_barrier
	s_add_i32 s69, 0, 0x18000
	v_add_u32_e32 v145, s69, v141
	s_add_i32 s70, 0, 0x1c000
	ds_read_b128 v[156:159], v145
	ds_read_b128 v[160:163], v145 offset:1024
	ds_read_b128 v[164:167], v145 offset:2048
	ds_read_b128 v[168:171], v145 offset:3072
	v_add_u32_e32 v145, s70, v141
	ds_read_b128 v[172:175], v145
	ds_read_b128 v[176:179], v145 offset:1024
	ds_read_b128 v[180:183], v145 offset:2048
	ds_read_b128 v[184:187], v145 offset:3072
	s_add_u32 s6, s6, s4
	s_addc_u32 s7, s7, s5
	s_mov_b32 m0, s27
	v_lshl_add_u64 v[248:249], s[6:7], 0, v[134:135]
	ds_read_b128 v[188:191], v143 offset:32768
	ds_read_b128 v[192:195], v143 offset:33792
	ds_read_b128 v[196:199], v143 offset:34816
	ds_read_b128 v[200:203], v143 offset:35840
	ds_read_b128 v[204:207], v143 offset:36864
	ds_read_b128 v[218:221], v143 offset:37888
	ds_read_b128 v[222:225], v143 offset:38912
	ds_read_b128 v[226:229], v143 offset:39936
	global_load_lds_dwordx4 v[248:249], off
	v_lshl_add_u64 v[248:249], s[6:7], 0, v[132:133]
	s_mov_b32 m0, s38
	s_nop 0
	global_load_lds_dwordx4 v[248:249], off
	s_waitcnt vmcnt(8)
	s_waitcnt lgkmcnt(0)
	s_barrier
	s_waitcnt lgkmcnt(0)
	v_mfma_f32_16x16x32_bf16 v[126:129], v[156:159], v[188:191], v[126:129]
	v_mfma_f32_16x16x32_bf16 v[122:125], v[164:167], v[188:191], v[122:125]
	v_mfma_f32_16x16x32_bf16 v[110:113], v[156:159], v[196:199], v[110:113]
	v_mfma_f32_16x16x32_bf16 v[106:109], v[164:167], v[196:199], v[106:109]
	v_mfma_f32_16x16x32_bf16 v[92:95], v[156:159], v[204:207], v[92:95]
	v_mfma_f32_16x16x32_bf16 v[88:91], v[164:167], v[204:207], v[88:91]
	v_mfma_f32_16x16x32_bf16 v[76:79], v[156:159], v[222:225], v[76:79]
	v_mfma_f32_16x16x32_bf16 v[72:75], v[164:167], v[222:225], v[72:75]
	v_mfma_f32_16x16x32_bf16 v[126:129], v[160:163], v[192:195], v[126:129]
	v_mfma_f32_16x16x32_bf16 v[122:125], v[168:171], v[192:195], v[122:125]
	v_mfma_f32_16x16x32_bf16 v[110:113], v[160:163], v[200:203], v[110:113]
	v_mfma_f32_16x16x32_bf16 v[106:109], v[168:171], v[200:203], v[106:109]
	v_mfma_f32_16x16x32_bf16 v[92:95], v[160:163], v[218:221], v[92:95]
	v_mfma_f32_16x16x32_bf16 v[88:91], v[168:171], v[218:221], v[88:91]
	v_mfma_f32_16x16x32_bf16 v[76:79], v[160:163], v[226:229], v[76:79]
	v_mfma_f32_16x16x32_bf16 v[72:75], v[168:171], v[226:229], v[72:75]
	v_mfma_f32_16x16x32_bf16 v[118:121], v[172:175], v[188:191], v[118:121]
	v_mfma_f32_16x16x32_bf16 v[114:117], v[180:183], v[188:191], v[114:117]
	v_mfma_f32_16x16x32_bf16 v[102:105], v[172:175], v[196:199], v[102:105]
	v_mfma_f32_16x16x32_bf16 v[98:101], v[180:183], v[196:199], v[98:101]
	v_mfma_f32_16x16x32_bf16 v[84:87], v[172:175], v[204:207], v[84:87]
	v_mfma_f32_16x16x32_bf16 v[80:83], v[180:183], v[204:207], v[80:83]
	v_mfma_f32_16x16x32_bf16 v[68:71], v[172:175], v[222:225], v[68:71]
	v_mfma_f32_16x16x32_bf16 v[64:67], v[180:183], v[222:225], v[64:67]
	v_mfma_f32_16x16x32_bf16 v[118:121], v[176:179], v[192:195], v[118:121]
	v_mfma_f32_16x16x32_bf16 v[114:117], v[184:187], v[192:195], v[114:117]
	v_mfma_f32_16x16x32_bf16 v[102:105], v[176:179], v[200:203], v[102:105]
	v_mfma_f32_16x16x32_bf16 v[98:101], v[184:187], v[200:203], v[98:101]
	v_mfma_f32_16x16x32_bf16 v[84:87], v[176:179], v[218:221], v[84:87]
	v_mfma_f32_16x16x32_bf16 v[80:83], v[184:187], v[218:221], v[80:83]
	v_mfma_f32_16x16x32_bf16 v[68:71], v[176:179], v[226:229], v[68:71]
	v_mfma_f32_16x16x32_bf16 v[64:67], v[184:187], v[226:229], v[64:67]
	s_barrier
; #define PG8_STAGE(bufoff, gbase, voff) do { _Pragma("unroll") for (int _i = 0; _i < 2; ++_i) \
;         __builtin_amdgcn_global_load_lds((const unsigned*)((const char*)(gbase) + (voff)[_i]), (PG8_LAS unsigned*)(lds + (bufoff) + ldsw + _i * 8192), 16, 0, 0); } while (0)
; #define PG8_LDA(dst, b, h) do { _Pragma("unroll") for (int m = 0; m < 4; ++m) _Pragma("unroll") for (int k = 0; k < 2; ++k) dst[m][k] = *(const PG8_LAS bf16x8*)(lds + PG8_SA(b, h) + aoff + m * 2048 + k * 1024); } while (0)
; #define PG8_MMA(ai, bj, At, Bt) do { __builtin_amdgcn_s_setprio(1); _Pragma("unroll") for (int m = 0; m < 4; ++m) _Pragma("unroll") for (int n = 0; n < 2; ++n) _Pragma("unroll") for (int k = 0; k < 2; ++k) \
;         acc[ai][bj][m][n] = __builtin_amdgcn_mfma_f32_16x16x32_bf16(Bt[n][k], At[m][k], acc[ai][bj][m][n], 0, 0, 0); __builtin_amdgcn_s_setprio(0); } while (0)
; #define PG8_WAIT_V(n) asm volatile("s_waitcnt vmcnt(" #n ")" ::: "memory")
; #define PG8_WAIT_L(n) asm volatile("s_waitcnt lgkmcnt(" #n ")" ::: "memory")
; #define PG8_BAR __builtin_amdgcn_s_barrier()
; #define PG8_SCHED __builtin_amdgcn_sched_barrier(0)
; template <class Epi>
; __device__ __forceinline__ void gemm_phase(PG8_LAS unsigned char* lds, const Gemm g, const StaticOrder& S, const Epi& E, const int wave_s) {
;     ...
;             PG8_LDA(At, 1, 1); PG8_STAGE(PG8_SB(1, 0), b3, voffB); PG8_STAGE(PG8_SB(1, 1), b3 + hstepB, voffB); PG8_STAGE(PG8_SA(1, 0), a3, voffA);
;             PG8_WAIT_V(8); PG8_WAIT_L(0); PG8_BAR; PG8_MMA(1, 0, At, B0); PG8_MMA(1, 1, At, B1); PG8_BAR; PG8_SCHED;
;         }
	s_add_i32 s6, s69, s9
	v_lshl_add_u64 v[208:209], v[208:209], 0, s[52:53]
	s_mov_b32 m0, s6
	ds_read_b128 v[188:191], v143 offset:49152
	ds_read_b128 v[192:195], v143 offset:50176
	ds_read_b128 v[196:199], v143 offset:51200
	ds_read_b128 v[200:203], v143 offset:52224
	ds_read_b128 v[204:207], v143 offset:53248
	ds_read_b128 v[218:221], v143 offset:54272
	ds_read_b128 v[222:225], v143 offset:55296
	ds_read_b128 v[226:229], v143 offset:56320
	global_load_lds_dwordx4 v[208:209], off
	v_lshl_add_u64 v[208:209], v[230:231], 0, s[52:53]
	s_add_i32 m0, s6, 0x2000
	s_add_i32 s6, s70, s9
	global_load_lds_dwordx4 v[208:209], off
	v_lshl_add_u64 v[208:209], v[232:233], 0, s[52:53]
	s_mov_b32 m0, s6
	s_nop 0
	global_load_lds_dwordx4 v[208:209], off
	v_lshl_add_u64 v[208:209], v[242:243], 0, s[52:53]
	s_add_i32 m0, s6, 0x2000
	s_nop 0
	global_load_lds_dwordx4 v[208:209], off
	v_lshl_add_u64 v[208:209], v[244:245], 0, s[52:53]
	s_mov_b32 m0, s39
	s_nop 0
	global_load_lds_dwordx4 v[208:209], off
	v_lshl_add_u64 v[208:209], v[246:247], 0, s[52:53]
	s_mov_b32 m0, s58
	s_nop 0
	global_load_lds_dwordx4 v[208:209], off
	s_waitcnt vmcnt(8)
	s_waitcnt lgkmcnt(0)
	s_barrier
	s_waitcnt lgkmcnt(0)
	v_mfma_f32_16x16x32_bf16 v[60:63], v[156:159], v[188:191], v[60:63]
	v_mfma_f32_16x16x32_bf16 v[56:59], v[164:167], v[188:191], v[56:59]
	s_add_u32 s56, s56, 0x100
	s_addc_u32 s57, s57, 0
	s_add_u32 s66, s66, 0x100
	s_addc_u32 s67, s67, 0
	s_mov_b32 s6, s68
	s_cmp_ge_i32 s68, s59
	v_mfma_f32_16x16x32_bf16 v[44:47], v[156:159], v[196:199], v[44:47]
	v_mfma_f32_16x16x32_bf16 v[40:43], v[164:167], v[196:199], v[40:43]
	v_mfma_f32_16x16x32_bf16 v[28:31], v[156:159], v[204:207], v[28:31]
	v_mfma_f32_16x16x32_bf16 v[24:27], v[164:167], v[204:207], v[24:27]
	v_mfma_f32_16x16x32_bf16 v[12:15], v[156:159], v[222:225], v[12:15]
	v_mfma_f32_16x16x32_bf16 v[8:11], v[164:167], v[222:225], v[8:11]
	v_mfma_f32_16x16x32_bf16 v[60:63], v[160:163], v[192:195], v[60:63]
	v_mfma_f32_16x16x32_bf16 v[56:59], v[168:171], v[192:195], v[56:59]
	v_mfma_f32_16x16x32_bf16 v[44:47], v[160:163], v[200:203], v[44:47]
	v_mfma_f32_16x16x32_bf16 v[40:43], v[168:171], v[200:203], v[40:43]
	v_mfma_f32_16x16x32_bf16 v[28:31], v[160:163], v[218:221], v[28:31]
	v_mfma_f32_16x16x32_bf16 v[24:27], v[168:171], v[218:221], v[24:27]
	v_mfma_f32_16x16x32_bf16 v[12:15], v[160:163], v[226:229], v[12:15]
	v_mfma_f32_16x16x32_bf16 v[8:11], v[168:171], v[226:229], v[8:11]
	v_mfma_f32_16x16x32_bf16 v[52:55], v[172:175], v[188:191], v[52:55]
	v_mfma_f32_16x16x32_bf16 v[48:51], v[180:183], v[188:191], v[48:51]
	v_mfma_f32_16x16x32_bf16 v[36:39], v[172:175], v[196:199], v[36:39]
	v_mfma_f32_16x16x32_bf16 v[32:35], v[180:183], v[196:199], v[32:35]
	v_mfma_f32_16x16x32_bf16 v[20:23], v[172:175], v[204:207], v[20:23]
	v_mfma_f32_16x16x32_bf16 v[16:19], v[180:183], v[204:207], v[16:19]
	v_mfma_f32_16x16x32_bf16 v[4:7], v[172:175], v[222:225], v[4:7]
	v_mfma_f32_16x16x32_bf16 v[0:3], v[180:183], v[222:225], v[0:3]
	v_mfma_f32_16x16x32_bf16 v[52:55], v[176:179], v[192:195], v[52:55]
	v_mfma_f32_16x16x32_bf16 v[48:51], v[184:187], v[192:195], v[48:51]
	v_mfma_f32_16x16x32_bf16 v[36:39], v[176:179], v[200:203], v[36:39]
	v_mfma_f32_16x16x32_bf16 v[32:35], v[184:187], v[200:203], v[32:35]
	v_mfma_f32_16x16x32_bf16 v[20:23], v[176:179], v[218:221], v[20:23]
	v_mfma_f32_16x16x32_bf16 v[16:19], v[184:187], v[218:221], v[16:19]
	v_mfma_f32_16x16x32_bf16 v[4:7], v[176:179], v[226:229], v[4:7]
	v_mfma_f32_16x16x32_bf16 v[0:3], v[184:187], v[226:229], v[0:3]
	s_barrier
	s_cbranch_scc0 .LBB0_950
